# P0 transposes: LDS-read -> cvt -> store ladder de-serialised (each ds_read2 issued 6 units ahead into a ring of temporaries, counted lgkmcnt waits) on top of the final candidate
# baseline (speedup 1.0000x reference)
.LBB0_35:
	v_add_u32_e32 v63, s1, v4
	v_add_u32_e32 v14, 0xfcb20000, v63
	v_lshl_add_u64 v[6:7], v[14:15], 2, v[2:3]
	v_add_u32_e32 v14, 0xfcb21000, v63
	v_lshl_add_u64 v[8:9], v[14:15], 2, v[2:3]
	v_add_u32_e32 v14, 0xfcb22000, v63
	v_lshl_add_u64 v[10:11], v[14:15], 2, v[2:3]
	v_add_u32_e32 v14, 0xfcb23000, v63
	v_lshl_add_u64 v[12:13], v[14:15], 2, v[2:3]
	v_add_u32_e32 v14, 0xfcb24000, v63
	v_lshl_add_u64 v[64:65], v[14:15], 2, v[2:3]
	v_add_u32_e32 v14, 0xfcb25000, v63
	v_lshl_add_u64 v[66:67], v[14:15], 2, v[2:3]
	v_add_u32_e32 v14, 0xfcb26000, v63
	v_lshl_add_u64 v[68:69], v[14:15], 2, v[2:3]
	v_add_u32_e32 v14, 0xfcb27000, v63
	global_load_dwordx2 v[6:7], v[6:7], off
	s_nop 0
	global_load_dwordx2 v[8:9], v[8:9], off
	v_lshl_add_u64 v[70:71], v[14:15], 2, v[2:3]
	global_load_dwordx2 v[10:11], v[10:11], off
	s_nop 0
	global_load_dwordx2 v[12:13], v[12:13], off
	s_nop 0
	global_load_dwordx2 v[64:65], v[64:65], off
	s_nop 0
	global_load_dwordx2 v[66:67], v[66:67], off
	s_nop 0
	global_load_dwordx2 v[68:69], v[68:69], off
	s_nop 0
	global_load_dwordx2 v[70:71], v[70:71], off
	s_add_i32 s1, s1, 0x8000
	v_add_u32_e32 v63, s1, v4
	v_add_u32_e32 v14, 0xfcb20000, v63
	v_lshl_add_u64 v[150:151], v[14:15], 2, v[2:3]
	v_add_u32_e32 v14, 0xfcb21000, v63
	v_lshl_add_u64 v[152:153], v[14:15], 2, v[2:3]
	v_add_u32_e32 v14, 0xfcb22000, v63
	v_lshl_add_u64 v[154:155], v[14:15], 2, v[2:3]
	v_add_u32_e32 v14, 0xfcb23000, v63
	v_lshl_add_u64 v[156:157], v[14:15], 2, v[2:3]
	v_add_u32_e32 v14, 0xfcb24000, v63
	v_lshl_add_u64 v[158:159], v[14:15], 2, v[2:3]
	v_add_u32_e32 v14, 0xfcb25000, v63
	v_lshl_add_u64 v[160:161], v[14:15], 2, v[2:3]
	v_add_u32_e32 v14, 0xfcb26000, v63
	v_lshl_add_u64 v[162:163], v[14:15], 2, v[2:3]
	v_add_u32_e32 v14, 0xfcb27000, v63
	global_load_dwordx2 v[150:151], v[150:151], off
	s_nop 0
	global_load_dwordx2 v[152:153], v[152:153], off
	v_lshl_add_u64 v[164:165], v[14:15], 2, v[2:3]
	global_load_dwordx2 v[154:155], v[154:155], off
	s_nop 0
	global_load_dwordx2 v[156:157], v[156:157], off
	s_nop 0
	global_load_dwordx2 v[158:159], v[158:159], off
	s_nop 0
	global_load_dwordx2 v[160:161], v[160:161], off
	s_nop 0
	global_load_dwordx2 v[162:163], v[162:163], off
	s_nop 0
	global_load_dwordx2 v[164:165], v[164:165], off
	s_add_i32 s1, s1, 0x8000
	v_add_u32_e32 v63, s1, v4
	v_add_u32_e32 v14, 0xfcb20000, v63
	v_lshl_add_u64 v[166:167], v[14:15], 2, v[2:3]
	v_add_u32_e32 v14, 0xfcb21000, v63
	v_lshl_add_u64 v[168:169], v[14:15], 2, v[2:3]
	v_add_u32_e32 v14, 0xfcb22000, v63
	v_lshl_add_u64 v[170:171], v[14:15], 2, v[2:3]
	v_add_u32_e32 v14, 0xfcb23000, v63
	v_lshl_add_u64 v[172:173], v[14:15], 2, v[2:3]
	v_add_u32_e32 v14, 0xfcb24000, v63
	v_lshl_add_u64 v[174:175], v[14:15], 2, v[2:3]
	v_add_u32_e32 v14, 0xfcb25000, v63
	v_lshl_add_u64 v[176:177], v[14:15], 2, v[2:3]
	v_add_u32_e32 v14, 0xfcb26000, v63
	v_lshl_add_u64 v[178:179], v[14:15], 2, v[2:3]
	v_add_u32_e32 v14, 0xfcb27000, v63
	global_load_dwordx2 v[166:167], v[166:167], off
	s_nop 0
	global_load_dwordx2 v[168:169], v[168:169], off
	v_lshl_add_u64 v[180:181], v[14:15], 2, v[2:3]
	global_load_dwordx2 v[170:171], v[170:171], off
	s_nop 0
	global_load_dwordx2 v[172:173], v[172:173], off
	s_nop 0
	global_load_dwordx2 v[174:175], v[174:175], off
	s_nop 0
	global_load_dwordx2 v[176:177], v[176:177], off
	s_nop 0
	global_load_dwordx2 v[178:179], v[178:179], off
	s_nop 0
	global_load_dwordx2 v[180:181], v[180:181], off
	s_add_i32 s1, s1, 0x8000
	v_add_u32_e32 v63, s1, v4
	v_add_u32_e32 v14, 0xfcb20000, v63
	v_lshl_add_u64 v[182:183], v[14:15], 2, v[2:3]
	v_add_u32_e32 v14, 0xfcb21000, v63
	v_lshl_add_u64 v[184:185], v[14:15], 2, v[2:3]
	v_add_u32_e32 v14, 0xfcb22000, v63
	v_lshl_add_u64 v[186:187], v[14:15], 2, v[2:3]
	v_add_u32_e32 v14, 0xfcb23000, v63
	v_lshl_add_u64 v[188:189], v[14:15], 2, v[2:3]
	v_add_u32_e32 v14, 0xfcb24000, v63
	v_lshl_add_u64 v[190:191], v[14:15], 2, v[2:3]
	v_add_u32_e32 v14, 0xfcb25000, v63
	v_lshl_add_u64 v[192:193], v[14:15], 2, v[2:3]
	v_add_u32_e32 v14, 0xfcb26000, v63
	v_lshl_add_u64 v[194:195], v[14:15], 2, v[2:3]
	v_add_u32_e32 v14, 0xfcb27000, v63
	global_load_dwordx2 v[182:183], v[182:183], off
	s_nop 0
	global_load_dwordx2 v[184:185], v[184:185], off
	v_lshl_add_u64 v[196:197], v[14:15], 2, v[2:3]
	global_load_dwordx2 v[186:187], v[186:187], off
	s_nop 0
	global_load_dwordx2 v[188:189], v[188:189], off
	s_nop 0
	global_load_dwordx2 v[190:191], v[190:191], off
	s_nop 0
	global_load_dwordx2 v[192:193], v[192:193], off
	s_nop 0
	global_load_dwordx2 v[194:195], v[194:195], off
	s_nop 0
	global_load_dwordx2 v[196:197], v[196:197], off
	s_add_i32 s1, s1, 0x8000
	v_add_u32_e32 v14, 0x410, v5
	v_add_u32_e32 v63, 0x618, v5
	v_add_u32_e32 v72, 0x820, v5
	v_add_u32_e32 v73, 0xa28, v5
	v_add_u32_e32 v74, 0xc30, v5
	v_add_u32_e32 v75, 0xe38, v5
	s_waitcnt vmcnt(31)
	ds_write2_b32 v5, v6, v7 offset1:1
	s_waitcnt vmcnt(30)
	ds_write2_b32 v5, v8, v9 offset0:130 offset1:131
	v_add_u32_e32 v5, 0x1040, v5
	s_waitcnt vmcnt(29)
	ds_write2_b32 v14, v10, v11 offset1:1
	s_waitcnt vmcnt(28)
	ds_write2_b32 v63, v12, v13 offset1:1
	s_waitcnt vmcnt(27)
	ds_write2_b32 v72, v64, v65 offset1:1
	s_waitcnt vmcnt(26)
	ds_write2_b32 v73, v66, v67 offset1:1
	s_waitcnt vmcnt(25)
	ds_write2_b32 v74, v68, v69 offset1:1
	s_waitcnt vmcnt(24)
	ds_write2_b32 v75, v70, v71 offset1:1
	v_add_u32_e32 v14, 0x410, v5
	v_add_u32_e32 v63, 0x618, v5
	v_add_u32_e32 v72, 0x820, v5
	v_add_u32_e32 v73, 0xa28, v5
	v_add_u32_e32 v74, 0xc30, v5
	v_add_u32_e32 v75, 0xe38, v5
	s_waitcnt vmcnt(23)
	ds_write2_b32 v5, v150, v151 offset1:1
	s_waitcnt vmcnt(22)
	ds_write2_b32 v5, v152, v153 offset0:130 offset1:131
	v_add_u32_e32 v5, 0x1040, v5
	s_waitcnt vmcnt(21)
	ds_write2_b32 v14, v154, v155 offset1:1
	s_waitcnt vmcnt(20)
	ds_write2_b32 v63, v156, v157 offset1:1
	s_waitcnt vmcnt(19)
	ds_write2_b32 v72, v158, v159 offset1:1
	s_waitcnt vmcnt(18)
	ds_write2_b32 v73, v160, v161 offset1:1
	s_waitcnt vmcnt(17)
	ds_write2_b32 v74, v162, v163 offset1:1
	s_waitcnt vmcnt(16)
	ds_write2_b32 v75, v164, v165 offset1:1
	v_add_u32_e32 v14, 0x410, v5
	v_add_u32_e32 v63, 0x618, v5
	v_add_u32_e32 v72, 0x820, v5
	v_add_u32_e32 v73, 0xa28, v5
	v_add_u32_e32 v74, 0xc30, v5
	v_add_u32_e32 v75, 0xe38, v5
	s_waitcnt vmcnt(15)
	ds_write2_b32 v5, v166, v167 offset1:1
	s_waitcnt vmcnt(14)
	ds_write2_b32 v5, v168, v169 offset0:130 offset1:131
	v_add_u32_e32 v5, 0x1040, v5
	s_waitcnt vmcnt(13)
	ds_write2_b32 v14, v170, v171 offset1:1
	s_waitcnt vmcnt(12)
	ds_write2_b32 v63, v172, v173 offset1:1
	s_waitcnt vmcnt(11)
	ds_write2_b32 v72, v174, v175 offset1:1
	s_waitcnt vmcnt(10)
	ds_write2_b32 v73, v176, v177 offset1:1
	s_waitcnt vmcnt(9)
	ds_write2_b32 v74, v178, v179 offset1:1
	s_waitcnt vmcnt(8)
	ds_write2_b32 v75, v180, v181 offset1:1
	v_add_u32_e32 v14, 0x410, v5
	v_add_u32_e32 v63, 0x618, v5
	v_add_u32_e32 v72, 0x820, v5
	v_add_u32_e32 v73, 0xa28, v5
	v_add_u32_e32 v74, 0xc30, v5
	v_add_u32_e32 v75, 0xe38, v5
	s_waitcnt vmcnt(7)
	ds_write2_b32 v5, v182, v183 offset1:1
	s_waitcnt vmcnt(6)
	ds_write2_b32 v5, v184, v185 offset0:130 offset1:131
	v_add_u32_e32 v5, 0x1040, v5
	s_waitcnt vmcnt(5)
	ds_write2_b32 v14, v186, v187 offset1:1
	s_waitcnt vmcnt(4)
	ds_write2_b32 v63, v188, v189 offset1:1
	s_waitcnt vmcnt(3)
	ds_write2_b32 v72, v190, v191 offset1:1
	s_waitcnt vmcnt(2)
	ds_write2_b32 v73, v192, v193 offset1:1
	s_waitcnt vmcnt(1)
	ds_write2_b32 v74, v194, v195 offset1:1
	s_waitcnt vmcnt(0)
	ds_write2_b32 v75, v196, v197 offset1:1
	s_waitcnt lgkmcnt(0)
	v_add_u32_e32 v12, 0x400, v81
	ds_read2_b32 v[216:217], v81 offset1:65
	ds_read2_b32 v[218:219], v81 offset0:130 offset1:195
	ds_read2_b32 v[220:221], v12 offset0:4 offset1:69
	ds_read2_b32 v[222:223], v12 offset0:134 offset1:199
	ds_read2_b32 v[224:225], v81 offset0:8 offset1:73
	ds_read2_b32 v[226:227], v81 offset0:138 offset1:203
	ds_read2_b32 v[228:229], v12 offset0:12 offset1:77
	s_waitcnt lgkmcnt(6)
	v_cvt_pk_bf16_f32 v2, v216, v217
	ds_read2_b32 v[230:231], v12 offset0:142 offset1:207
	s_waitcnt lgkmcnt(6)
	v_cvt_pk_bf16_f32 v3, v218, v219
	ds_read2_b32 v[216:217], v81 offset0:16 offset1:81
	s_lshl_b32 s1, s96, 1
	s_waitcnt lgkmcnt(6)
	v_cvt_pk_bf16_f32 v4, v220, v221
	v_or_b32_e32 v5, s0, v80
	s_and_b32 s1, s1, 0x7fc0
	v_mul_u32_u24_e32 v8, 0x1600, v5
	s_add_i32 s8, s1, 0xffff9640
	v_lshlrev_b32_e32 v14, 1, v8
	v_lshl_add_u64 v[8:9], s[8:9], 1, v[22:23]
	v_lshl_add_u64 v[10:11], v[8:9], 0, v[14:15]
	ds_read2_b32 v[218:219], v81 offset0:146 offset1:211
	s_waitcnt lgkmcnt(6)
	v_cvt_pk_bf16_f32 v5, v222, v223
	global_store_dwordx4 v[10:11], v[2:5], off
	v_or_b32_e32 v10, s0, v82
	v_mul_u32_u24_e32 v10, 0x1600, v10
	ds_read2_b32 v[220:221], v12 offset0:20 offset1:85
	s_waitcnt lgkmcnt(6)
	v_cvt_pk_bf16_f32 v2, v224, v225
	ds_read2_b32 v[222:223], v12 offset0:150 offset1:215
	v_lshlrev_b32_e32 v14, 1, v10
	s_waitcnt lgkmcnt(6)
	v_cvt_pk_bf16_f32 v3, v226, v227
	ds_read2_b32 v[224:225], v81 offset0:24 offset1:89
	v_lshl_add_u64 v[10:11], v[8:9], 0, v[14:15]
	s_waitcnt lgkmcnt(6)
	v_cvt_pk_bf16_f32 v4, v228, v229
	ds_read2_b32 v[226:227], v81 offset0:154 offset1:219
	s_waitcnt lgkmcnt(6)
	v_cvt_pk_bf16_f32 v5, v230, v231
	global_store_dwordx4 v[10:11], v[2:5], off
	v_or_b32_e32 v10, s0, v83
	v_mul_u32_u24_e32 v10, 0x1600, v10
	ds_read2_b32 v[228:229], v12 offset0:28 offset1:93
	s_waitcnt lgkmcnt(6)
	v_cvt_pk_bf16_f32 v2, v216, v217
	ds_read2_b32 v[230:231], v12 offset0:158 offset1:223
	v_lshlrev_b32_e32 v14, 1, v10
	s_waitcnt lgkmcnt(6)
	v_cvt_pk_bf16_f32 v3, v218, v219
	ds_read2_b32 v[216:217], v81 offset0:32 offset1:97
	v_lshl_add_u64 v[10:11], v[8:9], 0, v[14:15]
	s_waitcnt lgkmcnt(6)
	v_cvt_pk_bf16_f32 v4, v220, v221
	ds_read2_b32 v[218:219], v81 offset0:162 offset1:227
	s_waitcnt lgkmcnt(6)
	v_cvt_pk_bf16_f32 v5, v222, v223
	global_store_dwordx4 v[10:11], v[2:5], off
	v_or_b32_e32 v10, s0, v84
	v_mul_u32_u24_e32 v10, 0x1600, v10
	ds_read2_b32 v[220:221], v12 offset0:36 offset1:101
	s_waitcnt lgkmcnt(6)
	v_cvt_pk_bf16_f32 v2, v224, v225
	ds_read2_b32 v[222:223], v12 offset0:166 offset1:231
	v_lshlrev_b32_e32 v14, 1, v10
	s_waitcnt lgkmcnt(6)
	v_cvt_pk_bf16_f32 v3, v226, v227
	ds_read2_b32 v[224:225], v81 offset0:40 offset1:105
	v_lshl_add_u64 v[10:11], v[8:9], 0, v[14:15]
	s_waitcnt lgkmcnt(6)
	v_cvt_pk_bf16_f32 v4, v228, v229
	ds_read2_b32 v[226:227], v81 offset0:170 offset1:235
	s_waitcnt lgkmcnt(6)
	v_cvt_pk_bf16_f32 v5, v230, v231
	global_store_dwordx4 v[10:11], v[2:5], off
	v_or_b32_e32 v10, s0, v85
	v_mul_u32_u24_e32 v10, 0x1600, v10
	ds_read2_b32 v[228:229], v12 offset0:44 offset1:109
	s_waitcnt lgkmcnt(6)
	v_cvt_pk_bf16_f32 v2, v216, v217
	ds_read2_b32 v[230:231], v12 offset0:174 offset1:239
	v_lshlrev_b32_e32 v14, 1, v10
	s_waitcnt lgkmcnt(6)
	v_cvt_pk_bf16_f32 v3, v218, v219
	ds_read2_b32 v[216:217], v81 offset0:48 offset1:113
	v_lshl_add_u64 v[10:11], v[8:9], 0, v[14:15]
	s_waitcnt lgkmcnt(6)
	v_cvt_pk_bf16_f32 v4, v220, v221
	ds_read2_b32 v[218:219], v81 offset0:178 offset1:243
	s_waitcnt lgkmcnt(6)
	v_cvt_pk_bf16_f32 v5, v222, v223
	global_store_dwordx4 v[10:11], v[2:5], off
	v_or_b32_e32 v10, s0, v86
	v_mul_u32_u24_e32 v10, 0x1600, v10
	ds_read2_b32 v[220:221], v12 offset0:52 offset1:117
	s_waitcnt lgkmcnt(6)
	v_cvt_pk_bf16_f32 v2, v224, v225
	ds_read2_b32 v[222:223], v12 offset0:182 offset1:247
	v_lshlrev_b32_e32 v14, 1, v10
	s_waitcnt lgkmcnt(6)
	v_cvt_pk_bf16_f32 v3, v226, v227
	ds_read2_b32 v[224:225], v81 offset0:56 offset1:121
	v_lshl_add_u64 v[10:11], v[8:9], 0, v[14:15]
	s_waitcnt lgkmcnt(6)
	v_cvt_pk_bf16_f32 v4, v228, v229
	ds_read2_b32 v[226:227], v81 offset0:186 offset1:251
	s_waitcnt lgkmcnt(6)
	v_cvt_pk_bf16_f32 v5, v230, v231
	global_store_dwordx4 v[10:11], v[2:5], off
	v_or_b32_e32 v10, s0, v87
	ds_read2_b32 v[228:229], v12 offset0:60 offset1:125
	s_waitcnt lgkmcnt(6)
	v_cvt_pk_bf16_f32 v2, v216, v217
	ds_read2_b32 v[230:231], v12 offset0:190 offset1:255
	v_mul_u32_u24_e32 v10, 0x1600, v10
	s_waitcnt lgkmcnt(6)
	v_cvt_pk_bf16_f32 v3, v218, v219
	v_lshlrev_b32_e32 v14, 1, v10
	s_waitcnt lgkmcnt(5)
	v_cvt_pk_bf16_f32 v4, v220, v221
	s_waitcnt lgkmcnt(4)
	v_cvt_pk_bf16_f32 v5, v222, v223
	v_lshl_add_u64 v[10:11], v[8:9], 0, v[14:15]
	global_store_dwordx4 v[10:11], v[2:5], off
	s_nop 0
	s_waitcnt lgkmcnt(3)
	v_cvt_pk_bf16_f32 v2, v224, v225
	s_waitcnt lgkmcnt(2)
	v_cvt_pk_bf16_f32 v3, v226, v227
	s_waitcnt lgkmcnt(1)
	v_cvt_pk_bf16_f32 v4, v228, v229
	v_or_b32_e32 v5, s0, v88
	v_mul_u32_u24_e32 v5, 0x1600, v5
	v_lshlrev_b32_e32 v14, 1, v5
	s_waitcnt lgkmcnt(0)
	v_cvt_pk_bf16_f32 v5, v230, v231
	v_lshl_add_u64 v[6:7], v[8:9], 0, v[14:15]
	global_store_dwordx4 v[6:7], v[2:5], off

.LBB0_40:
	v_lshl_add_u64 v[66:67], v[10:11], 0, s[0:1]
	v_add_co_u32_e32 v76, vcc, 0xb000, v66
	v_lshl_add_u64 v[64:65], v[12:13], 0, s[0:1]
	s_nop 0
	v_addc_co_u32_e32 v77, vcc, 0, v67, vcc
	v_add_co_u32_e32 v108, vcc, 0x16000, v66
	v_lshl_add_u64 v[68:69], v[8:9], 0, s[0:1]
	s_nop 0
	v_addc_co_u32_e32 v109, vcc, 0, v67, vcc
	v_lshl_add_u64 v[70:71], v[6:7], 0, s[0:1]
	v_lshl_add_u64 v[72:73], v[4:5], 0, s[0:1]
	v_lshl_add_u64 v[74:75], v[2:3], 0, s[0:1]
	v_add_co_u32_e32 v66, vcc, 0x21000, v66
	global_load_dwordx2 v[64:65], v[64:65], off
	s_nop 0
	global_load_dwordx2 v[68:69], v[68:69], off
	s_nop 0
	global_load_dwordx2 v[70:71], v[70:71], off
	s_nop 0
	global_load_dwordx2 v[72:73], v[72:73], off
	s_nop 0
	global_load_dwordx2 v[74:75], v[74:75], off
	v_addc_co_u32_e32 v67, vcc, 0, v67, vcc
	global_load_dwordx2 v[76:77], v[76:77], off
	s_nop 0
	global_load_dwordx2 v[108:109], v[108:109], off
	s_nop 0
	global_load_dwordx2 v[66:67], v[66:67], off
	s_add_u32 s0, s0, 0x58000
	s_addc_u32 s1, s1, 0
	v_lshl_add_u64 v[164:165], v[10:11], 0, s[0:1]
	v_add_co_u32_e32 v160, vcc, 0xb000, v164
	v_lshl_add_u64 v[150:151], v[12:13], 0, s[0:1]
	s_nop 0
	v_addc_co_u32_e32 v161, vcc, 0, v165, vcc
	v_add_co_u32_e32 v162, vcc, 0x16000, v164
	v_lshl_add_u64 v[152:153], v[8:9], 0, s[0:1]
	s_nop 0
	v_addc_co_u32_e32 v163, vcc, 0, v165, vcc
	v_lshl_add_u64 v[154:155], v[6:7], 0, s[0:1]
	v_lshl_add_u64 v[156:157], v[4:5], 0, s[0:1]
	v_lshl_add_u64 v[158:159], v[2:3], 0, s[0:1]
	v_add_co_u32_e32 v164, vcc, 0x21000, v164
	global_load_dwordx2 v[150:151], v[150:151], off
	s_nop 0
	global_load_dwordx2 v[152:153], v[152:153], off
	s_nop 0
	global_load_dwordx2 v[154:155], v[154:155], off
	s_nop 0
	global_load_dwordx2 v[156:157], v[156:157], off
	s_nop 0
	global_load_dwordx2 v[158:159], v[158:159], off
	v_addc_co_u32_e32 v165, vcc, 0, v165, vcc
	global_load_dwordx2 v[160:161], v[160:161], off
	s_nop 0
	global_load_dwordx2 v[162:163], v[162:163], off
	s_nop 0
	global_load_dwordx2 v[164:165], v[164:165], off
	s_add_u32 s0, s0, 0x58000
	s_addc_u32 s1, s1, 0
	v_lshl_add_u64 v[180:181], v[10:11], 0, s[0:1]
	v_add_co_u32_e32 v176, vcc, 0xb000, v180
	v_lshl_add_u64 v[166:167], v[12:13], 0, s[0:1]
	s_nop 0
	v_addc_co_u32_e32 v177, vcc, 0, v181, vcc
	v_add_co_u32_e32 v178, vcc, 0x16000, v180
	v_lshl_add_u64 v[168:169], v[8:9], 0, s[0:1]
	s_nop 0
	v_addc_co_u32_e32 v179, vcc, 0, v181, vcc
	v_lshl_add_u64 v[170:171], v[6:7], 0, s[0:1]
	v_lshl_add_u64 v[172:173], v[4:5], 0, s[0:1]
	v_lshl_add_u64 v[174:175], v[2:3], 0, s[0:1]
	v_add_co_u32_e32 v180, vcc, 0x21000, v180
	global_load_dwordx2 v[166:167], v[166:167], off
	s_nop 0
	global_load_dwordx2 v[168:169], v[168:169], off
	s_nop 0
	global_load_dwordx2 v[170:171], v[170:171], off
	s_nop 0
	global_load_dwordx2 v[172:173], v[172:173], off
	s_nop 0
	global_load_dwordx2 v[174:175], v[174:175], off
	v_addc_co_u32_e32 v181, vcc, 0, v181, vcc
	global_load_dwordx2 v[176:177], v[176:177], off
	s_nop 0
	global_load_dwordx2 v[178:179], v[178:179], off
	s_nop 0
	global_load_dwordx2 v[180:181], v[180:181], off
	s_add_u32 s0, s0, 0x58000
	s_addc_u32 s1, s1, 0
	v_lshl_add_u64 v[196:197], v[10:11], 0, s[0:1]
	v_add_co_u32_e32 v192, vcc, 0xb000, v196
	v_lshl_add_u64 v[182:183], v[12:13], 0, s[0:1]
	s_nop 0
	v_addc_co_u32_e32 v193, vcc, 0, v197, vcc
	v_add_co_u32_e32 v194, vcc, 0x16000, v196
	v_lshl_add_u64 v[184:185], v[8:9], 0, s[0:1]
	s_nop 0
	v_addc_co_u32_e32 v195, vcc, 0, v197, vcc
	v_lshl_add_u64 v[186:187], v[6:7], 0, s[0:1]
	v_lshl_add_u64 v[188:189], v[4:5], 0, s[0:1]
	v_lshl_add_u64 v[190:191], v[2:3], 0, s[0:1]
	v_add_co_u32_e32 v196, vcc, 0x21000, v196
	global_load_dwordx2 v[182:183], v[182:183], off
	s_nop 0
	global_load_dwordx2 v[184:185], v[184:185], off
	s_nop 0
	global_load_dwordx2 v[186:187], v[186:187], off
	s_nop 0
	global_load_dwordx2 v[188:189], v[188:189], off
	s_nop 0
	global_load_dwordx2 v[190:191], v[190:191], off
	v_addc_co_u32_e32 v197, vcc, 0, v197, vcc
	global_load_dwordx2 v[192:193], v[192:193], off
	s_nop 0
	global_load_dwordx2 v[194:195], v[194:195], off
	s_nop 0
	global_load_dwordx2 v[196:197], v[196:197], off
	s_add_u32 s0, s0, 0x58000
	s_addc_u32 s1, s1, 0
	v_add_u32_e32 v63, 0x410, v14
	v_add_u32_e32 v110, 0x618, v14
	v_add_u32_e32 v111, 0x820, v14
	v_add_u32_e32 v112, 0xa28, v14
	v_add_u32_e32 v113, 0xc30, v14
	v_add_u32_e32 v114, 0xe38, v14
	s_waitcnt vmcnt(31)
	ds_write2_b32 v14, v64, v65 offset1:1
	s_waitcnt vmcnt(30)
	ds_write2_b32 v111, v68, v69 offset1:1
	s_waitcnt vmcnt(29)
	ds_write2_b32 v112, v70, v71 offset1:1
	s_waitcnt vmcnt(28)
	ds_write2_b32 v113, v72, v73 offset1:1
	s_waitcnt vmcnt(27)
	ds_write2_b32 v114, v74, v75 offset1:1
	s_waitcnt vmcnt(26)
	ds_write2_b32 v14, v76, v77 offset0:130 offset1:131
	v_add_u32_e32 v14, 0x1040, v14
	s_waitcnt vmcnt(25)
	ds_write2_b32 v63, v108, v109 offset1:1
	s_waitcnt vmcnt(24)
	ds_write2_b32 v110, v66, v67 offset1:1
	v_add_u32_e32 v63, 0x410, v14
	v_add_u32_e32 v110, 0x618, v14
	v_add_u32_e32 v111, 0x820, v14
	v_add_u32_e32 v112, 0xa28, v14
	v_add_u32_e32 v113, 0xc30, v14
	v_add_u32_e32 v114, 0xe38, v14
	s_waitcnt vmcnt(23)
	ds_write2_b32 v14, v150, v151 offset1:1
	s_waitcnt vmcnt(22)
	ds_write2_b32 v111, v152, v153 offset1:1
	s_waitcnt vmcnt(21)
	ds_write2_b32 v112, v154, v155 offset1:1
	s_waitcnt vmcnt(20)
	ds_write2_b32 v113, v156, v157 offset1:1
	s_waitcnt vmcnt(19)
	ds_write2_b32 v114, v158, v159 offset1:1
	s_waitcnt vmcnt(18)
	ds_write2_b32 v14, v160, v161 offset0:130 offset1:131
	v_add_u32_e32 v14, 0x1040, v14
	s_waitcnt vmcnt(17)
	ds_write2_b32 v63, v162, v163 offset1:1
	s_waitcnt vmcnt(16)
	ds_write2_b32 v110, v164, v165 offset1:1
	v_add_u32_e32 v63, 0x410, v14
	v_add_u32_e32 v110, 0x618, v14
	v_add_u32_e32 v111, 0x820, v14
	v_add_u32_e32 v112, 0xa28, v14
	v_add_u32_e32 v113, 0xc30, v14
	v_add_u32_e32 v114, 0xe38, v14
	s_waitcnt vmcnt(15)
	ds_write2_b32 v14, v166, v167 offset1:1
	s_waitcnt vmcnt(14)
	ds_write2_b32 v111, v168, v169 offset1:1
	s_waitcnt vmcnt(13)
	ds_write2_b32 v112, v170, v171 offset1:1
	s_waitcnt vmcnt(12)
	ds_write2_b32 v113, v172, v173 offset1:1
	s_waitcnt vmcnt(11)
	ds_write2_b32 v114, v174, v175 offset1:1
	s_waitcnt vmcnt(10)
	ds_write2_b32 v14, v176, v177 offset0:130 offset1:131
	v_add_u32_e32 v14, 0x1040, v14
	s_waitcnt vmcnt(9)
	ds_write2_b32 v63, v178, v179 offset1:1
	s_waitcnt vmcnt(8)
	ds_write2_b32 v110, v180, v181 offset1:1
	v_add_u32_e32 v63, 0x410, v14
	v_add_u32_e32 v110, 0x618, v14
	v_add_u32_e32 v111, 0x820, v14
	v_add_u32_e32 v112, 0xa28, v14
	v_add_u32_e32 v113, 0xc30, v14
	v_add_u32_e32 v114, 0xe38, v14
	s_waitcnt vmcnt(7)
	ds_write2_b32 v14, v182, v183 offset1:1
	s_waitcnt vmcnt(6)
	ds_write2_b32 v111, v184, v185 offset1:1
	s_waitcnt vmcnt(5)
	ds_write2_b32 v112, v186, v187 offset1:1
	s_waitcnt vmcnt(4)
	ds_write2_b32 v113, v188, v189 offset1:1
	s_waitcnt vmcnt(3)
	ds_write2_b32 v114, v190, v191 offset1:1
	s_waitcnt vmcnt(2)
	ds_write2_b32 v14, v192, v193 offset0:130 offset1:131
	v_add_u32_e32 v14, 0x1040, v14
	s_waitcnt vmcnt(1)
	ds_write2_b32 v63, v194, v195 offset1:1
	s_waitcnt vmcnt(0)
	ds_write2_b32 v110, v196, v197 offset1:1
	s_lshl_b32 s0, s2, 7
	s_and_b32 s1, s3, 64
	s_waitcnt lgkmcnt(0)
	s_or_b32 s0, s1, s0
	v_add_u32_e32 v12, 0x400, v81
	ds_read2_b32 v[216:217], v81 offset1:65
	ds_read2_b32 v[218:219], v81 offset0:130 offset1:195
	ds_read2_b32 v[220:221], v12 offset0:4 offset1:69
	ds_read2_b32 v[222:223], v12 offset0:134 offset1:199
	ds_read2_b32 v[224:225], v81 offset0:8 offset1:73
	ds_read2_b32 v[226:227], v81 offset0:138 offset1:203
	ds_read2_b32 v[228:229], v12 offset0:12 offset1:77
	s_and_b32 s2, 0xffff, s4
	s_bitset1_b32 s0, 7
	s_waitcnt lgkmcnt(6)
	v_cvt_pk_bf16_f32 v2, v216, v217
	ds_read2_b32 v[230:231], v12 offset0:142 offset1:207
	s_lshl_b32 s8, s2, 1
	v_or_b32_e32 v10, s0, v80
	s_waitcnt lgkmcnt(6)
	v_cvt_pk_bf16_f32 v3, v218, v219
	ds_read2_b32 v[216:217], v81 offset0:16 offset1:81
	v_lshl_add_u64 v[8:9], v[24:25], 0, s[8:9]
	v_lshlrev_b32_e32 v14, 12, v10
	s_waitcnt lgkmcnt(6)
	v_cvt_pk_bf16_f32 v4, v220, v221
	ds_read2_b32 v[218:219], v81 offset0:146 offset1:211
	s_waitcnt lgkmcnt(6)
	v_cvt_pk_bf16_f32 v5, v222, v223
	v_lshl_add_u64 v[10:11], v[8:9], 0, v[14:15]
	ds_read2_b32 v[220:221], v12 offset0:20 offset1:85
	global_store_dwordx4 v[10:11], v[2:5], off
	v_or_b32_e32 v10, s0, v82
	v_lshlrev_b32_e32 v14, 12, v10
	s_waitcnt lgkmcnt(6)
	v_cvt_pk_bf16_f32 v2, v224, v225
	ds_read2_b32 v[222:223], v12 offset0:150 offset1:215
	s_waitcnt lgkmcnt(6)
	v_cvt_pk_bf16_f32 v3, v226, v227
	ds_read2_b32 v[224:225], v81 offset0:24 offset1:89
	s_waitcnt lgkmcnt(6)
	v_cvt_pk_bf16_f32 v4, v228, v229
	ds_read2_b32 v[226:227], v81 offset0:154 offset1:219
	s_waitcnt lgkmcnt(6)
	v_cvt_pk_bf16_f32 v5, v230, v231
	v_lshl_add_u64 v[10:11], v[8:9], 0, v[14:15]
	ds_read2_b32 v[228:229], v12 offset0:28 offset1:93
	global_store_dwordx4 v[10:11], v[2:5], off
	v_or_b32_e32 v10, s0, v83
	v_lshlrev_b32_e32 v14, 12, v10
	s_waitcnt lgkmcnt(6)
	v_cvt_pk_bf16_f32 v2, v216, v217
	ds_read2_b32 v[230:231], v12 offset0:158 offset1:223
	s_waitcnt lgkmcnt(6)
	v_cvt_pk_bf16_f32 v3, v218, v219
	ds_read2_b32 v[216:217], v81 offset0:32 offset1:97
	s_waitcnt lgkmcnt(6)
	v_cvt_pk_bf16_f32 v4, v220, v221
	ds_read2_b32 v[218:219], v81 offset0:162 offset1:227
	s_waitcnt lgkmcnt(6)
	v_cvt_pk_bf16_f32 v5, v222, v223
	v_lshl_add_u64 v[10:11], v[8:9], 0, v[14:15]
	ds_read2_b32 v[220:221], v12 offset0:36 offset1:101
	global_store_dwordx4 v[10:11], v[2:5], off
	v_or_b32_e32 v10, s0, v84
	v_lshlrev_b32_e32 v14, 12, v10
	s_waitcnt lgkmcnt(6)
	v_cvt_pk_bf16_f32 v2, v224, v225
	ds_read2_b32 v[222:223], v12 offset0:166 offset1:231
	s_waitcnt lgkmcnt(6)
	v_cvt_pk_bf16_f32 v3, v226, v227
	ds_read2_b32 v[224:225], v81 offset0:40 offset1:105
	s_waitcnt lgkmcnt(6)
	v_cvt_pk_bf16_f32 v4, v228, v229
	ds_read2_b32 v[226:227], v81 offset0:170 offset1:235
	s_waitcnt lgkmcnt(6)
	v_cvt_pk_bf16_f32 v5, v230, v231
	v_lshl_add_u64 v[10:11], v[8:9], 0, v[14:15]
	ds_read2_b32 v[228:229], v12 offset0:44 offset1:109
	global_store_dwordx4 v[10:11], v[2:5], off
	v_or_b32_e32 v10, s0, v85
	v_lshlrev_b32_e32 v14, 12, v10
	s_waitcnt lgkmcnt(6)
	v_cvt_pk_bf16_f32 v2, v216, v217
	ds_read2_b32 v[230:231], v12 offset0:174 offset1:239
	s_waitcnt lgkmcnt(6)
	v_cvt_pk_bf16_f32 v3, v218, v219
	ds_read2_b32 v[216:217], v81 offset0:48 offset1:113
	s_waitcnt lgkmcnt(6)
	v_cvt_pk_bf16_f32 v4, v220, v221
	ds_read2_b32 v[218:219], v81 offset0:178 offset1:243
	s_waitcnt lgkmcnt(6)
	v_cvt_pk_bf16_f32 v5, v222, v223
	v_lshl_add_u64 v[10:11], v[8:9], 0, v[14:15]
	ds_read2_b32 v[220:221], v12 offset0:52 offset1:117
	global_store_dwordx4 v[10:11], v[2:5], off
	v_or_b32_e32 v10, s0, v86
	v_lshlrev_b32_e32 v14, 12, v10
	s_waitcnt lgkmcnt(6)
	v_cvt_pk_bf16_f32 v2, v224, v225
	ds_read2_b32 v[222:223], v12 offset0:182 offset1:247
	s_waitcnt lgkmcnt(6)
	v_cvt_pk_bf16_f32 v3, v226, v227
	ds_read2_b32 v[224:225], v81 offset0:56 offset1:121
	s_waitcnt lgkmcnt(6)
	v_cvt_pk_bf16_f32 v4, v228, v229
	ds_read2_b32 v[226:227], v81 offset0:186 offset1:251
	s_waitcnt lgkmcnt(6)
	v_cvt_pk_bf16_f32 v5, v230, v231
	v_lshl_add_u64 v[10:11], v[8:9], 0, v[14:15]
	ds_read2_b32 v[228:229], v12 offset0:60 offset1:125
	global_store_dwordx4 v[10:11], v[2:5], off
	v_or_b32_e32 v10, s0, v87
	v_lshlrev_b32_e32 v14, 12, v10
	s_waitcnt lgkmcnt(6)
	v_cvt_pk_bf16_f32 v2, v216, v217
	ds_read2_b32 v[230:231], v12 offset0:190 offset1:255
	s_waitcnt lgkmcnt(6)
	v_cvt_pk_bf16_f32 v3, v218, v219
	s_waitcnt lgkmcnt(5)
	v_cvt_pk_bf16_f32 v4, v220, v221
	s_waitcnt lgkmcnt(4)
	v_cvt_pk_bf16_f32 v5, v222, v223
	v_lshl_add_u64 v[10:11], v[8:9], 0, v[14:15]
	global_store_dwordx4 v[10:11], v[2:5], off
	s_nop 0
	s_waitcnt lgkmcnt(3)
	v_cvt_pk_bf16_f32 v2, v224, v225
	s_waitcnt lgkmcnt(2)
	v_cvt_pk_bf16_f32 v3, v226, v227
	s_waitcnt lgkmcnt(1)
	v_cvt_pk_bf16_f32 v4, v228, v229
	v_or_b32_e32 v5, s0, v88
	v_lshlrev_b32_e32 v14, 12, v5
	s_waitcnt lgkmcnt(0)
	v_cvt_pk_bf16_f32 v5, v230, v231
	v_lshl_add_u64 v[6:7], v[8:9], 0, v[14:15]
	global_store_dwordx4 v[6:7], v[2:5], off

.LBB0_45:
	v_lshl_add_u64 v[66:67], v[10:11], 0, s[0:1]
	v_add_co_u32_e32 v76, vcc, 0xb000, v66
	v_lshl_add_u64 v[64:65], v[12:13], 0, s[0:1]
	s_nop 0
	v_addc_co_u32_e32 v77, vcc, 0, v67, vcc
	v_add_co_u32_e32 v108, vcc, 0x16000, v66
	v_lshl_add_u64 v[68:69], v[8:9], 0, s[0:1]
	s_nop 0
	v_addc_co_u32_e32 v109, vcc, 0, v67, vcc
	v_lshl_add_u64 v[70:71], v[6:7], 0, s[0:1]
	v_lshl_add_u64 v[72:73], v[4:5], 0, s[0:1]
	v_lshl_add_u64 v[74:75], v[2:3], 0, s[0:1]
	v_add_co_u32_e32 v66, vcc, 0x21000, v66
	global_load_dwordx2 v[64:65], v[64:65], off
	s_nop 0
	global_load_dwordx2 v[68:69], v[68:69], off
	s_nop 0
	global_load_dwordx2 v[70:71], v[70:71], off
	s_nop 0
	global_load_dwordx2 v[72:73], v[72:73], off
	s_nop 0
	global_load_dwordx2 v[74:75], v[74:75], off
	v_addc_co_u32_e32 v67, vcc, 0, v67, vcc
	global_load_dwordx2 v[76:77], v[76:77], off
	s_nop 0
	global_load_dwordx2 v[108:109], v[108:109], off
	s_nop 0
	global_load_dwordx2 v[66:67], v[66:67], off
	s_add_u32 s0, s0, 0x58000
	s_addc_u32 s1, s1, 0
	v_lshl_add_u64 v[164:165], v[10:11], 0, s[0:1]
	v_add_co_u32_e32 v160, vcc, 0xb000, v164
	v_lshl_add_u64 v[150:151], v[12:13], 0, s[0:1]
	s_nop 0
	v_addc_co_u32_e32 v161, vcc, 0, v165, vcc
	v_add_co_u32_e32 v162, vcc, 0x16000, v164
	v_lshl_add_u64 v[152:153], v[8:9], 0, s[0:1]
	s_nop 0
	v_addc_co_u32_e32 v163, vcc, 0, v165, vcc
	v_lshl_add_u64 v[154:155], v[6:7], 0, s[0:1]
	v_lshl_add_u64 v[156:157], v[4:5], 0, s[0:1]
	v_lshl_add_u64 v[158:159], v[2:3], 0, s[0:1]
	v_add_co_u32_e32 v164, vcc, 0x21000, v164
	global_load_dwordx2 v[150:151], v[150:151], off
	s_nop 0
	global_load_dwordx2 v[152:153], v[152:153], off
	s_nop 0
	global_load_dwordx2 v[154:155], v[154:155], off
	s_nop 0
	global_load_dwordx2 v[156:157], v[156:157], off
	s_nop 0
	global_load_dwordx2 v[158:159], v[158:159], off
	v_addc_co_u32_e32 v165, vcc, 0, v165, vcc
	global_load_dwordx2 v[160:161], v[160:161], off
	s_nop 0
	global_load_dwordx2 v[162:163], v[162:163], off
	s_nop 0
	global_load_dwordx2 v[164:165], v[164:165], off
	s_add_u32 s0, s0, 0x58000
	s_addc_u32 s1, s1, 0
	v_lshl_add_u64 v[180:181], v[10:11], 0, s[0:1]
	v_add_co_u32_e32 v176, vcc, 0xb000, v180
	v_lshl_add_u64 v[166:167], v[12:13], 0, s[0:1]
	s_nop 0
	v_addc_co_u32_e32 v177, vcc, 0, v181, vcc
	v_add_co_u32_e32 v178, vcc, 0x16000, v180
	v_lshl_add_u64 v[168:169], v[8:9], 0, s[0:1]
	s_nop 0
	v_addc_co_u32_e32 v179, vcc, 0, v181, vcc
	v_lshl_add_u64 v[170:171], v[6:7], 0, s[0:1]
	v_lshl_add_u64 v[172:173], v[4:5], 0, s[0:1]
	v_lshl_add_u64 v[174:175], v[2:3], 0, s[0:1]
	v_add_co_u32_e32 v180, vcc, 0x21000, v180
	global_load_dwordx2 v[166:167], v[166:167], off
	s_nop 0
	global_load_dwordx2 v[168:169], v[168:169], off
	s_nop 0
	global_load_dwordx2 v[170:171], v[170:171], off
	s_nop 0
	global_load_dwordx2 v[172:173], v[172:173], off
	s_nop 0
	global_load_dwordx2 v[174:175], v[174:175], off
	v_addc_co_u32_e32 v181, vcc, 0, v181, vcc
	global_load_dwordx2 v[176:177], v[176:177], off
	s_nop 0
	global_load_dwordx2 v[178:179], v[178:179], off
	s_nop 0
	global_load_dwordx2 v[180:181], v[180:181], off
	s_add_u32 s0, s0, 0x58000
	s_addc_u32 s1, s1, 0
	v_lshl_add_u64 v[196:197], v[10:11], 0, s[0:1]
	v_add_co_u32_e32 v192, vcc, 0xb000, v196
	v_lshl_add_u64 v[182:183], v[12:13], 0, s[0:1]
	s_nop 0
	v_addc_co_u32_e32 v193, vcc, 0, v197, vcc
	v_add_co_u32_e32 v194, vcc, 0x16000, v196
	v_lshl_add_u64 v[184:185], v[8:9], 0, s[0:1]
	s_nop 0
	v_addc_co_u32_e32 v195, vcc, 0, v197, vcc
	v_lshl_add_u64 v[186:187], v[6:7], 0, s[0:1]
	v_lshl_add_u64 v[188:189], v[4:5], 0, s[0:1]
	v_lshl_add_u64 v[190:191], v[2:3], 0, s[0:1]
	v_add_co_u32_e32 v196, vcc, 0x21000, v196
	global_load_dwordx2 v[182:183], v[182:183], off
	s_nop 0
	global_load_dwordx2 v[184:185], v[184:185], off
	s_nop 0
	global_load_dwordx2 v[186:187], v[186:187], off
	s_nop 0
	global_load_dwordx2 v[188:189], v[188:189], off
	s_nop 0
	global_load_dwordx2 v[190:191], v[190:191], off
	v_addc_co_u32_e32 v197, vcc, 0, v197, vcc
	global_load_dwordx2 v[192:193], v[192:193], off
	s_nop 0
	global_load_dwordx2 v[194:195], v[194:195], off
	s_nop 0
	global_load_dwordx2 v[196:197], v[196:197], off
	s_add_u32 s0, s0, 0x58000
	s_addc_u32 s1, s1, 0
	v_add_u32_e32 v63, 0x410, v14
	v_add_u32_e32 v110, 0x618, v14
	v_add_u32_e32 v111, 0x820, v14
	v_add_u32_e32 v112, 0xa28, v14
	v_add_u32_e32 v113, 0xc30, v14
	v_add_u32_e32 v114, 0xe38, v14
	s_waitcnt vmcnt(31)
	ds_write2_b32 v14, v64, v65 offset1:1
	s_waitcnt vmcnt(30)
	ds_write2_b32 v111, v68, v69 offset1:1
	s_waitcnt vmcnt(29)
	ds_write2_b32 v112, v70, v71 offset1:1
	s_waitcnt vmcnt(28)
	ds_write2_b32 v113, v72, v73 offset1:1
	s_waitcnt vmcnt(27)
	ds_write2_b32 v114, v74, v75 offset1:1
	s_waitcnt vmcnt(26)
	ds_write2_b32 v14, v76, v77 offset0:130 offset1:131
	v_add_u32_e32 v14, 0x1040, v14
	s_waitcnt vmcnt(25)
	ds_write2_b32 v63, v108, v109 offset1:1
	s_waitcnt vmcnt(24)
	ds_write2_b32 v110, v66, v67 offset1:1
	v_add_u32_e32 v63, 0x410, v14
	v_add_u32_e32 v110, 0x618, v14
	v_add_u32_e32 v111, 0x820, v14
	v_add_u32_e32 v112, 0xa28, v14
	v_add_u32_e32 v113, 0xc30, v14
	v_add_u32_e32 v114, 0xe38, v14
	s_waitcnt vmcnt(23)
	ds_write2_b32 v14, v150, v151 offset1:1
	s_waitcnt vmcnt(22)
	ds_write2_b32 v111, v152, v153 offset1:1
	s_waitcnt vmcnt(21)
	ds_write2_b32 v112, v154, v155 offset1:1
	s_waitcnt vmcnt(20)
	ds_write2_b32 v113, v156, v157 offset1:1
	s_waitcnt vmcnt(19)
	ds_write2_b32 v114, v158, v159 offset1:1
	s_waitcnt vmcnt(18)
	ds_write2_b32 v14, v160, v161 offset0:130 offset1:131
	v_add_u32_e32 v14, 0x1040, v14
	s_waitcnt vmcnt(17)
	ds_write2_b32 v63, v162, v163 offset1:1
	s_waitcnt vmcnt(16)
	ds_write2_b32 v110, v164, v165 offset1:1
	v_add_u32_e32 v63, 0x410, v14
	v_add_u32_e32 v110, 0x618, v14
	v_add_u32_e32 v111, 0x820, v14
	v_add_u32_e32 v112, 0xa28, v14
	v_add_u32_e32 v113, 0xc30, v14
	v_add_u32_e32 v114, 0xe38, v14
	s_waitcnt vmcnt(15)
	ds_write2_b32 v14, v166, v167 offset1:1
	s_waitcnt vmcnt(14)
	ds_write2_b32 v111, v168, v169 offset1:1
	s_waitcnt vmcnt(13)
	ds_write2_b32 v112, v170, v171 offset1:1
	s_waitcnt vmcnt(12)
	ds_write2_b32 v113, v172, v173 offset1:1
	s_waitcnt vmcnt(11)
	ds_write2_b32 v114, v174, v175 offset1:1
	s_waitcnt vmcnt(10)
	ds_write2_b32 v14, v176, v177 offset0:130 offset1:131
	v_add_u32_e32 v14, 0x1040, v14
	s_waitcnt vmcnt(9)
	ds_write2_b32 v63, v178, v179 offset1:1
	s_waitcnt vmcnt(8)
	ds_write2_b32 v110, v180, v181 offset1:1
	v_add_u32_e32 v63, 0x410, v14
	v_add_u32_e32 v110, 0x618, v14
	v_add_u32_e32 v111, 0x820, v14
	v_add_u32_e32 v112, 0xa28, v14
	v_add_u32_e32 v113, 0xc30, v14
	v_add_u32_e32 v114, 0xe38, v14
	s_waitcnt vmcnt(7)
	ds_write2_b32 v14, v182, v183 offset1:1
	s_waitcnt vmcnt(6)
	ds_write2_b32 v111, v184, v185 offset1:1
	s_waitcnt vmcnt(5)
	ds_write2_b32 v112, v186, v187 offset1:1
	s_waitcnt vmcnt(4)
	ds_write2_b32 v113, v188, v189 offset1:1
	s_waitcnt vmcnt(3)
	ds_write2_b32 v114, v190, v191 offset1:1
	s_waitcnt vmcnt(2)
	ds_write2_b32 v14, v192, v193 offset0:130 offset1:131
	v_add_u32_e32 v14, 0x1040, v14
	s_waitcnt vmcnt(1)
	ds_write2_b32 v63, v194, v195 offset1:1
	s_waitcnt vmcnt(0)
	ds_write2_b32 v110, v196, v197 offset1:1
	s_lshl_b32 s0, s2, 7
	s_waitcnt lgkmcnt(0)
	s_and_b32 s1, s3, 64
	s_and_b32 s0, s0, 0x3f00
	v_add_u32_e32 v12, 0x400, v81
	ds_read2_b32 v[216:217], v81 offset1:65
	ds_read2_b32 v[218:219], v81 offset0:130 offset1:195
	ds_read2_b32 v[220:221], v12 offset0:4 offset1:69
	ds_read2_b32 v[222:223], v12 offset0:134 offset1:199
	ds_read2_b32 v[224:225], v81 offset0:8 offset1:73
	ds_read2_b32 v[226:227], v81 offset0:138 offset1:203
	ds_read2_b32 v[228:229], v12 offset0:12 offset1:77
	s_and_b32 s2, 0xffff, s4
	s_or_b32 s0, s0, s1
	s_waitcnt lgkmcnt(6)
	v_cvt_pk_bf16_f32 v2, v216, v217
	ds_read2_b32 v[230:231], v12 offset0:142 offset1:207
	s_lshl_b32 s8, s2, 1
	v_or_b32_e32 v10, s0, v80
	s_waitcnt lgkmcnt(6)
	v_cvt_pk_bf16_f32 v3, v218, v219
	ds_read2_b32 v[216:217], v81 offset0:16 offset1:81
	v_lshl_add_u64 v[8:9], v[24:25], 0, s[8:9]
	v_lshlrev_b32_e32 v14, 12, v10
	s_waitcnt lgkmcnt(6)
	v_cvt_pk_bf16_f32 v4, v220, v221
	ds_read2_b32 v[218:219], v81 offset0:146 offset1:211
	s_waitcnt lgkmcnt(6)
	v_cvt_pk_bf16_f32 v5, v222, v223
	v_lshl_add_u64 v[10:11], v[8:9], 0, v[14:15]
	ds_read2_b32 v[220:221], v12 offset0:20 offset1:85
	global_store_dwordx4 v[10:11], v[2:5], off
	v_or_b32_e32 v10, s0, v82
	v_lshlrev_b32_e32 v14, 12, v10
	s_waitcnt lgkmcnt(6)
	v_cvt_pk_bf16_f32 v2, v224, v225
	ds_read2_b32 v[222:223], v12 offset0:150 offset1:215
	s_waitcnt lgkmcnt(6)
	v_cvt_pk_bf16_f32 v3, v226, v227
	ds_read2_b32 v[224:225], v81 offset0:24 offset1:89
	s_waitcnt lgkmcnt(6)
	v_cvt_pk_bf16_f32 v4, v228, v229
	ds_read2_b32 v[226:227], v81 offset0:154 offset1:219
	s_waitcnt lgkmcnt(6)
	v_cvt_pk_bf16_f32 v5, v230, v231
	v_lshl_add_u64 v[10:11], v[8:9], 0, v[14:15]
	ds_read2_b32 v[228:229], v12 offset0:28 offset1:93
	global_store_dwordx4 v[10:11], v[2:5], off
	v_or_b32_e32 v10, s0, v83
	v_lshlrev_b32_e32 v14, 12, v10
	s_waitcnt lgkmcnt(6)
	v_cvt_pk_bf16_f32 v2, v216, v217
	ds_read2_b32 v[230:231], v12 offset0:158 offset1:223
	s_waitcnt lgkmcnt(6)
	v_cvt_pk_bf16_f32 v3, v218, v219
	ds_read2_b32 v[216:217], v81 offset0:32 offset1:97
	s_waitcnt lgkmcnt(6)
	v_cvt_pk_bf16_f32 v4, v220, v221
	ds_read2_b32 v[218:219], v81 offset0:162 offset1:227
	s_waitcnt lgkmcnt(6)
	v_cvt_pk_bf16_f32 v5, v222, v223
	v_lshl_add_u64 v[10:11], v[8:9], 0, v[14:15]
	ds_read2_b32 v[220:221], v12 offset0:36 offset1:101
	global_store_dwordx4 v[10:11], v[2:5], off
	v_or_b32_e32 v10, s0, v84
	v_lshlrev_b32_e32 v14, 12, v10
	s_waitcnt lgkmcnt(6)
	v_cvt_pk_bf16_f32 v2, v224, v225
	ds_read2_b32 v[222:223], v12 offset0:166 offset1:231
	s_waitcnt lgkmcnt(6)
	v_cvt_pk_bf16_f32 v3, v226, v227
	ds_read2_b32 v[224:225], v81 offset0:40 offset1:105
	s_waitcnt lgkmcnt(6)
	v_cvt_pk_bf16_f32 v4, v228, v229
	ds_read2_b32 v[226:227], v81 offset0:170 offset1:235
	s_waitcnt lgkmcnt(6)
	v_cvt_pk_bf16_f32 v5, v230, v231
	v_lshl_add_u64 v[10:11], v[8:9], 0, v[14:15]
	ds_read2_b32 v[228:229], v12 offset0:44 offset1:109
	global_store_dwordx4 v[10:11], v[2:5], off
	v_or_b32_e32 v10, s0, v85
	v_lshlrev_b32_e32 v14, 12, v10
	s_waitcnt lgkmcnt(6)
	v_cvt_pk_bf16_f32 v2, v216, v217
	ds_read2_b32 v[230:231], v12 offset0:174 offset1:239
	s_waitcnt lgkmcnt(6)
	v_cvt_pk_bf16_f32 v3, v218, v219
	ds_read2_b32 v[216:217], v81 offset0:48 offset1:113
	s_waitcnt lgkmcnt(6)
	v_cvt_pk_bf16_f32 v4, v220, v221
	ds_read2_b32 v[218:219], v81 offset0:178 offset1:243
	s_waitcnt lgkmcnt(6)
	v_cvt_pk_bf16_f32 v5, v222, v223
	v_lshl_add_u64 v[10:11], v[8:9], 0, v[14:15]
	ds_read2_b32 v[220:221], v12 offset0:52 offset1:117
	global_store_dwordx4 v[10:11], v[2:5], off
	v_or_b32_e32 v10, s0, v86
	v_lshlrev_b32_e32 v14, 12, v10
	s_waitcnt lgkmcnt(6)
	v_cvt_pk_bf16_f32 v2, v224, v225
	ds_read2_b32 v[222:223], v12 offset0:182 offset1:247
	s_waitcnt lgkmcnt(6)
	v_cvt_pk_bf16_f32 v3, v226, v227
	ds_read2_b32 v[224:225], v81 offset0:56 offset1:121
	s_waitcnt lgkmcnt(6)
	v_cvt_pk_bf16_f32 v4, v228, v229
	ds_read2_b32 v[226:227], v81 offset0:186 offset1:251
	s_waitcnt lgkmcnt(6)
	v_cvt_pk_bf16_f32 v5, v230, v231
	v_lshl_add_u64 v[10:11], v[8:9], 0, v[14:15]
	ds_read2_b32 v[228:229], v12 offset0:60 offset1:125
	global_store_dwordx4 v[10:11], v[2:5], off
	v_or_b32_e32 v10, s0, v87
	v_lshlrev_b32_e32 v14, 12, v10
	s_waitcnt lgkmcnt(6)
	v_cvt_pk_bf16_f32 v2, v216, v217
	ds_read2_b32 v[230:231], v12 offset0:190 offset1:255
	s_waitcnt lgkmcnt(6)
	v_cvt_pk_bf16_f32 v3, v218, v219
	s_waitcnt lgkmcnt(5)
	v_cvt_pk_bf16_f32 v4, v220, v221
	s_waitcnt lgkmcnt(4)
	v_cvt_pk_bf16_f32 v5, v222, v223
	v_lshl_add_u64 v[10:11], v[8:9], 0, v[14:15]
	global_store_dwordx4 v[10:11], v[2:5], off
	s_nop 0
	s_waitcnt lgkmcnt(3)
	v_cvt_pk_bf16_f32 v2, v224, v225
	s_waitcnt lgkmcnt(2)
	v_cvt_pk_bf16_f32 v3, v226, v227
	s_waitcnt lgkmcnt(1)
	v_cvt_pk_bf16_f32 v4, v228, v229
	v_or_b32_e32 v5, s0, v88
	v_lshlrev_b32_e32 v14, 12, v5
	s_waitcnt lgkmcnt(0)
	v_cvt_pk_bf16_f32 v5, v230, v231
	v_lshl_add_u64 v[6:7], v[8:9], 0, v[14:15]
	global_store_dwordx4 v[6:7], v[2:5], off

.LBB0_50:
	v_add_u32_e32 v5, s1, v62
	v_add_u32_e32 v14, 0xfe520000, v5
	v_lshl_add_u64 v[6:7], v[14:15], 2, v[2:3]
	v_add_u32_e32 v14, 0xfe521000, v5
	v_lshl_add_u64 v[8:9], v[14:15], 2, v[2:3]
	v_add_u32_e32 v14, 0xfe522000, v5
	v_lshl_add_u64 v[10:11], v[14:15], 2, v[2:3]
	v_add_u32_e32 v14, 0xfe523000, v5
	v_lshl_add_u64 v[12:13], v[14:15], 2, v[2:3]
	v_add_u32_e32 v14, 0xfe524000, v5
	v_lshl_add_u64 v[64:65], v[14:15], 2, v[2:3]
	v_add_u32_e32 v14, 0xfe525000, v5
	v_lshl_add_u64 v[66:67], v[14:15], 2, v[2:3]
	v_add_u32_e32 v14, 0xfe526000, v5
	v_lshl_add_u64 v[68:69], v[14:15], 2, v[2:3]
	v_add_u32_e32 v14, 0xfe527000, v5
	global_load_dwordx2 v[6:7], v[6:7], off
	s_nop 0
	global_load_dwordx2 v[8:9], v[8:9], off
	v_lshl_add_u64 v[70:71], v[14:15], 2, v[2:3]
	global_load_dwordx2 v[10:11], v[10:11], off
	s_nop 0
	global_load_dwordx2 v[12:13], v[12:13], off
	s_nop 0
	global_load_dwordx2 v[64:65], v[64:65], off
	s_nop 0
	global_load_dwordx2 v[66:67], v[66:67], off
	s_nop 0
	global_load_dwordx2 v[68:69], v[68:69], off
	s_nop 0
	global_load_dwordx2 v[70:71], v[70:71], off
	s_add_i32 s1, s1, 0x8000
	v_add_u32_e32 v5, s1, v62
	v_add_u32_e32 v14, 0xfe520000, v5
	v_lshl_add_u64 v[150:151], v[14:15], 2, v[2:3]
	v_add_u32_e32 v14, 0xfe521000, v5
	v_lshl_add_u64 v[152:153], v[14:15], 2, v[2:3]
	v_add_u32_e32 v14, 0xfe522000, v5
	v_lshl_add_u64 v[154:155], v[14:15], 2, v[2:3]
	v_add_u32_e32 v14, 0xfe523000, v5
	v_lshl_add_u64 v[156:157], v[14:15], 2, v[2:3]
	v_add_u32_e32 v14, 0xfe524000, v5
	v_lshl_add_u64 v[158:159], v[14:15], 2, v[2:3]
	v_add_u32_e32 v14, 0xfe525000, v5
	v_lshl_add_u64 v[160:161], v[14:15], 2, v[2:3]
	v_add_u32_e32 v14, 0xfe526000, v5
	v_lshl_add_u64 v[162:163], v[14:15], 2, v[2:3]
	v_add_u32_e32 v14, 0xfe527000, v5
	global_load_dwordx2 v[150:151], v[150:151], off
	s_nop 0
	global_load_dwordx2 v[152:153], v[152:153], off
	v_lshl_add_u64 v[164:165], v[14:15], 2, v[2:3]
	global_load_dwordx2 v[154:155], v[154:155], off
	s_nop 0
	global_load_dwordx2 v[156:157], v[156:157], off
	s_nop 0
	global_load_dwordx2 v[158:159], v[158:159], off
	s_nop 0
	global_load_dwordx2 v[160:161], v[160:161], off
	s_nop 0
	global_load_dwordx2 v[162:163], v[162:163], off
	s_nop 0
	global_load_dwordx2 v[164:165], v[164:165], off
	s_add_i32 s1, s1, 0x8000
	v_add_u32_e32 v5, s1, v62
	v_add_u32_e32 v14, 0xfe520000, v5
	v_lshl_add_u64 v[166:167], v[14:15], 2, v[2:3]
	v_add_u32_e32 v14, 0xfe521000, v5
	v_lshl_add_u64 v[168:169], v[14:15], 2, v[2:3]
	v_add_u32_e32 v14, 0xfe522000, v5
	v_lshl_add_u64 v[170:171], v[14:15], 2, v[2:3]
	v_add_u32_e32 v14, 0xfe523000, v5
	v_lshl_add_u64 v[172:173], v[14:15], 2, v[2:3]
	v_add_u32_e32 v14, 0xfe524000, v5
	v_lshl_add_u64 v[174:175], v[14:15], 2, v[2:3]
	v_add_u32_e32 v14, 0xfe525000, v5
	v_lshl_add_u64 v[176:177], v[14:15], 2, v[2:3]
	v_add_u32_e32 v14, 0xfe526000, v5
	v_lshl_add_u64 v[178:179], v[14:15], 2, v[2:3]
	v_add_u32_e32 v14, 0xfe527000, v5
	global_load_dwordx2 v[166:167], v[166:167], off
	s_nop 0
	global_load_dwordx2 v[168:169], v[168:169], off
	v_lshl_add_u64 v[180:181], v[14:15], 2, v[2:3]
	global_load_dwordx2 v[170:171], v[170:171], off
	s_nop 0
	global_load_dwordx2 v[172:173], v[172:173], off
	s_nop 0
	global_load_dwordx2 v[174:175], v[174:175], off
	s_nop 0
	global_load_dwordx2 v[176:177], v[176:177], off
	s_nop 0
	global_load_dwordx2 v[178:179], v[178:179], off
	s_nop 0
	global_load_dwordx2 v[180:181], v[180:181], off
	s_add_i32 s1, s1, 0x8000
	v_add_u32_e32 v5, s1, v62
	v_add_u32_e32 v14, 0xfe520000, v5
	v_lshl_add_u64 v[182:183], v[14:15], 2, v[2:3]
	v_add_u32_e32 v14, 0xfe521000, v5
	v_lshl_add_u64 v[184:185], v[14:15], 2, v[2:3]
	v_add_u32_e32 v14, 0xfe522000, v5
	v_lshl_add_u64 v[186:187], v[14:15], 2, v[2:3]
	v_add_u32_e32 v14, 0xfe523000, v5
	v_lshl_add_u64 v[188:189], v[14:15], 2, v[2:3]
	v_add_u32_e32 v14, 0xfe524000, v5
	v_lshl_add_u64 v[190:191], v[14:15], 2, v[2:3]
	v_add_u32_e32 v14, 0xfe525000, v5
	v_lshl_add_u64 v[192:193], v[14:15], 2, v[2:3]
	v_add_u32_e32 v14, 0xfe526000, v5
	v_lshl_add_u64 v[194:195], v[14:15], 2, v[2:3]
	v_add_u32_e32 v14, 0xfe527000, v5
	global_load_dwordx2 v[182:183], v[182:183], off
	s_nop 0
	global_load_dwordx2 v[184:185], v[184:185], off
	v_lshl_add_u64 v[196:197], v[14:15], 2, v[2:3]
	global_load_dwordx2 v[186:187], v[186:187], off
	s_nop 0
	global_load_dwordx2 v[188:189], v[188:189], off
	s_nop 0
	global_load_dwordx2 v[190:191], v[190:191], off
	s_nop 0
	global_load_dwordx2 v[192:193], v[192:193], off
	s_nop 0
	global_load_dwordx2 v[194:195], v[194:195], off
	s_nop 0
	global_load_dwordx2 v[196:197], v[196:197], off
	s_add_i32 s1, s1, 0x8000
	v_add_u32_e32 v5, 0x410, v4
	v_add_u32_e32 v14, 0x618, v4
	v_add_u32_e32 v63, 0x820, v4
	v_add_u32_e32 v72, 0xa28, v4
	v_add_u32_e32 v73, 0xc30, v4
	v_add_u32_e32 v74, 0xe38, v4
	s_waitcnt vmcnt(31)
	ds_write2_b32 v4, v6, v7 offset1:1
	s_waitcnt vmcnt(30)
	ds_write2_b32 v4, v8, v9 offset0:130 offset1:131
	v_add_u32_e32 v4, 0x1040, v4
	s_waitcnt vmcnt(29)
	ds_write2_b32 v5, v10, v11 offset1:1
	s_waitcnt vmcnt(28)
	ds_write2_b32 v14, v12, v13 offset1:1
	s_waitcnt vmcnt(27)
	ds_write2_b32 v63, v64, v65 offset1:1
	s_waitcnt vmcnt(26)
	ds_write2_b32 v72, v66, v67 offset1:1
	s_waitcnt vmcnt(25)
	ds_write2_b32 v73, v68, v69 offset1:1
	s_waitcnt vmcnt(24)
	ds_write2_b32 v74, v70, v71 offset1:1
	v_add_u32_e32 v5, 0x410, v4
	v_add_u32_e32 v14, 0x618, v4
	v_add_u32_e32 v63, 0x820, v4
	v_add_u32_e32 v72, 0xa28, v4
	v_add_u32_e32 v73, 0xc30, v4
	v_add_u32_e32 v74, 0xe38, v4
	s_waitcnt vmcnt(23)
	ds_write2_b32 v4, v150, v151 offset1:1
	s_waitcnt vmcnt(22)
	ds_write2_b32 v4, v152, v153 offset0:130 offset1:131
	v_add_u32_e32 v4, 0x1040, v4
	s_waitcnt vmcnt(21)
	ds_write2_b32 v5, v154, v155 offset1:1
	s_waitcnt vmcnt(20)
	ds_write2_b32 v14, v156, v157 offset1:1
	s_waitcnt vmcnt(19)
	ds_write2_b32 v63, v158, v159 offset1:1
	s_waitcnt vmcnt(18)
	ds_write2_b32 v72, v160, v161 offset1:1
	s_waitcnt vmcnt(17)
	ds_write2_b32 v73, v162, v163 offset1:1
	s_waitcnt vmcnt(16)
	ds_write2_b32 v74, v164, v165 offset1:1
	v_add_u32_e32 v5, 0x410, v4
	v_add_u32_e32 v14, 0x618, v4
	v_add_u32_e32 v63, 0x820, v4
	v_add_u32_e32 v72, 0xa28, v4
	v_add_u32_e32 v73, 0xc30, v4
	v_add_u32_e32 v74, 0xe38, v4
	s_waitcnt vmcnt(15)
	ds_write2_b32 v4, v166, v167 offset1:1
	s_waitcnt vmcnt(14)
	ds_write2_b32 v4, v168, v169 offset0:130 offset1:131
	v_add_u32_e32 v4, 0x1040, v4
	s_waitcnt vmcnt(13)
	ds_write2_b32 v5, v170, v171 offset1:1
	s_waitcnt vmcnt(12)
	ds_write2_b32 v14, v172, v173 offset1:1
	s_waitcnt vmcnt(11)
	ds_write2_b32 v63, v174, v175 offset1:1
	s_waitcnt vmcnt(10)
	ds_write2_b32 v72, v176, v177 offset1:1
	s_waitcnt vmcnt(9)
	ds_write2_b32 v73, v178, v179 offset1:1
	s_waitcnt vmcnt(8)
	ds_write2_b32 v74, v180, v181 offset1:1
	v_add_u32_e32 v5, 0x410, v4
	v_add_u32_e32 v14, 0x618, v4
	v_add_u32_e32 v63, 0x820, v4
	v_add_u32_e32 v72, 0xa28, v4
	v_add_u32_e32 v73, 0xc30, v4
	v_add_u32_e32 v74, 0xe38, v4
	s_waitcnt vmcnt(7)
	ds_write2_b32 v4, v182, v183 offset1:1
	s_waitcnt vmcnt(6)
	ds_write2_b32 v4, v184, v185 offset0:130 offset1:131
	v_add_u32_e32 v4, 0x1040, v4
	s_waitcnt vmcnt(5)
	ds_write2_b32 v5, v186, v187 offset1:1
	s_waitcnt vmcnt(4)
	ds_write2_b32 v14, v188, v189 offset1:1
	s_waitcnt vmcnt(3)
	ds_write2_b32 v63, v190, v191 offset1:1
	s_waitcnt vmcnt(2)
	ds_write2_b32 v72, v192, v193 offset1:1
	s_waitcnt vmcnt(1)
	ds_write2_b32 v73, v194, v195 offset1:1
	s_waitcnt vmcnt(0)
	ds_write2_b32 v74, v196, v197 offset1:1
	s_waitcnt lgkmcnt(0)
	v_add_u32_e32 v12, 0x400, v81
	ds_read2_b32 v[216:217], v81 offset1:65
	ds_read2_b32 v[218:219], v81 offset0:130 offset1:195
	ds_read2_b32 v[220:221], v12 offset0:4 offset1:69
	ds_read2_b32 v[222:223], v12 offset0:134 offset1:199
	ds_read2_b32 v[224:225], v81 offset0:8 offset1:73
	ds_read2_b32 v[226:227], v81 offset0:138 offset1:203
	ds_read2_b32 v[228:229], v12 offset0:12 offset1:77
	s_waitcnt lgkmcnt(6)
	v_cvt_pk_bf16_f32 v2, v216, v217
	ds_read2_b32 v[230:231], v12 offset0:142 offset1:207
	s_lshl_b32 s1, s96, 1
	s_waitcnt lgkmcnt(6)
	v_cvt_pk_bf16_f32 v3, v218, v219
	ds_read2_b32 v[216:217], v81 offset0:16 offset1:81
	s_and_b32 s1, s1, 0x3fc0
	s_waitcnt lgkmcnt(6)
	v_cvt_pk_bf16_f32 v4, v220, v221
	v_or_b32_e32 v5, s0, v80
	s_add_i32 s8, s1, 0xffffca40
	v_lshlrev_b32_e32 v14, 12, v5
	v_lshl_add_u64 v[8:9], s[8:9], 1, v[28:29]
	ds_read2_b32 v[218:219], v81 offset0:146 offset1:211
	s_waitcnt lgkmcnt(6)
	v_cvt_pk_bf16_f32 v5, v222, v223
	v_lshl_add_u64 v[10:11], v[8:9], 0, v[14:15]
	ds_read2_b32 v[220:221], v12 offset0:20 offset1:85
	global_store_dwordx4 v[10:11], v[2:5], off
	v_or_b32_e32 v10, s0, v82
	v_lshlrev_b32_e32 v14, 12, v10
	s_waitcnt lgkmcnt(6)
	v_cvt_pk_bf16_f32 v2, v224, v225
	ds_read2_b32 v[222:223], v12 offset0:150 offset1:215
	s_waitcnt lgkmcnt(6)
	v_cvt_pk_bf16_f32 v3, v226, v227
	ds_read2_b32 v[224:225], v81 offset0:24 offset1:89
	s_waitcnt lgkmcnt(6)
	v_cvt_pk_bf16_f32 v4, v228, v229
	ds_read2_b32 v[226:227], v81 offset0:154 offset1:219
	s_waitcnt lgkmcnt(6)
	v_cvt_pk_bf16_f32 v5, v230, v231
	v_lshl_add_u64 v[10:11], v[8:9], 0, v[14:15]
	ds_read2_b32 v[228:229], v12 offset0:28 offset1:93
	global_store_dwordx4 v[10:11], v[2:5], off
	v_or_b32_e32 v10, s0, v83
	v_lshlrev_b32_e32 v14, 12, v10
	s_waitcnt lgkmcnt(6)
	v_cvt_pk_bf16_f32 v2, v216, v217
	ds_read2_b32 v[230:231], v12 offset0:158 offset1:223
	s_waitcnt lgkmcnt(6)
	v_cvt_pk_bf16_f32 v3, v218, v219
	ds_read2_b32 v[216:217], v81 offset0:32 offset1:97
	s_waitcnt lgkmcnt(6)
	v_cvt_pk_bf16_f32 v4, v220, v221
	ds_read2_b32 v[218:219], v81 offset0:162 offset1:227
	s_waitcnt lgkmcnt(6)
	v_cvt_pk_bf16_f32 v5, v222, v223
	v_lshl_add_u64 v[10:11], v[8:9], 0, v[14:15]
	ds_read2_b32 v[220:221], v12 offset0:36 offset1:101
	global_store_dwordx4 v[10:11], v[2:5], off
	v_or_b32_e32 v10, s0, v84
	v_lshlrev_b32_e32 v14, 12, v10
	s_waitcnt lgkmcnt(6)
	v_cvt_pk_bf16_f32 v2, v224, v225
	ds_read2_b32 v[222:223], v12 offset0:166 offset1:231
	s_waitcnt lgkmcnt(6)
	v_cvt_pk_bf16_f32 v3, v226, v227
	ds_read2_b32 v[224:225], v81 offset0:40 offset1:105
	s_waitcnt lgkmcnt(6)
	v_cvt_pk_bf16_f32 v4, v228, v229
	ds_read2_b32 v[226:227], v81 offset0:170 offset1:235
	s_waitcnt lgkmcnt(6)
	v_cvt_pk_bf16_f32 v5, v230, v231
	v_lshl_add_u64 v[10:11], v[8:9], 0, v[14:15]
	ds_read2_b32 v[228:229], v12 offset0:44 offset1:109
	global_store_dwordx4 v[10:11], v[2:5], off
	v_or_b32_e32 v10, s0, v85
	v_lshlrev_b32_e32 v14, 12, v10
	s_waitcnt lgkmcnt(6)
	v_cvt_pk_bf16_f32 v2, v216, v217
	ds_read2_b32 v[230:231], v12 offset0:174 offset1:239
	s_waitcnt lgkmcnt(6)
	v_cvt_pk_bf16_f32 v3, v218, v219
	ds_read2_b32 v[216:217], v81 offset0:48 offset1:113
	s_waitcnt lgkmcnt(6)
	v_cvt_pk_bf16_f32 v4, v220, v221
	ds_read2_b32 v[218:219], v81 offset0:178 offset1:243
	s_waitcnt lgkmcnt(6)
	v_cvt_pk_bf16_f32 v5, v222, v223
	v_lshl_add_u64 v[10:11], v[8:9], 0, v[14:15]
	ds_read2_b32 v[220:221], v12 offset0:52 offset1:117
	global_store_dwordx4 v[10:11], v[2:5], off
	v_or_b32_e32 v10, s0, v86
	v_lshlrev_b32_e32 v14, 12, v10
	s_waitcnt lgkmcnt(6)
	v_cvt_pk_bf16_f32 v2, v224, v225
	ds_read2_b32 v[222:223], v12 offset0:182 offset1:247
	s_waitcnt lgkmcnt(6)
	v_cvt_pk_bf16_f32 v3, v226, v227
	ds_read2_b32 v[224:225], v81 offset0:56 offset1:121
	s_waitcnt lgkmcnt(6)
	v_cvt_pk_bf16_f32 v4, v228, v229
	ds_read2_b32 v[226:227], v81 offset0:186 offset1:251
	s_waitcnt lgkmcnt(6)
	v_cvt_pk_bf16_f32 v5, v230, v231
	v_lshl_add_u64 v[10:11], v[8:9], 0, v[14:15]
	ds_read2_b32 v[228:229], v12 offset0:60 offset1:125
	global_store_dwordx4 v[10:11], v[2:5], off
	v_or_b32_e32 v10, s0, v87
	v_lshlrev_b32_e32 v14, 12, v10
	s_waitcnt lgkmcnt(6)
	v_cvt_pk_bf16_f32 v2, v216, v217
	ds_read2_b32 v[230:231], v12 offset0:190 offset1:255
	s_waitcnt lgkmcnt(6)
	v_cvt_pk_bf16_f32 v3, v218, v219
	s_waitcnt lgkmcnt(5)
	v_cvt_pk_bf16_f32 v4, v220, v221
	s_waitcnt lgkmcnt(4)
	v_cvt_pk_bf16_f32 v5, v222, v223
	v_lshl_add_u64 v[10:11], v[8:9], 0, v[14:15]
	global_store_dwordx4 v[10:11], v[2:5], off
	s_nop 0
	s_waitcnt lgkmcnt(3)
	v_cvt_pk_bf16_f32 v2, v224, v225
	s_waitcnt lgkmcnt(2)
	v_cvt_pk_bf16_f32 v3, v226, v227
	s_waitcnt lgkmcnt(1)
	v_cvt_pk_bf16_f32 v4, v228, v229
	v_or_b32_e32 v5, s0, v88
	v_lshlrev_b32_e32 v14, 12, v5
	s_waitcnt lgkmcnt(0)
	v_cvt_pk_bf16_f32 v5, v230, v231
	v_lshl_add_u64 v[6:7], v[8:9], 0, v[14:15]
	global_store_dwordx4 v[6:7], v[2:5], off

.LBB0_55:
	v_add_u32_e32 v5, s1, v62
	v_add_u32_e32 v14, 0xfe720000, v5
	v_lshl_add_u64 v[6:7], v[14:15], 2, v[2:3]
	v_add_u32_e32 v14, 0xfe721000, v5
	v_lshl_add_u64 v[8:9], v[14:15], 2, v[2:3]
	v_add_u32_e32 v14, 0xfe722000, v5
	v_lshl_add_u64 v[10:11], v[14:15], 2, v[2:3]
	v_add_u32_e32 v14, 0xfe723000, v5
	v_lshl_add_u64 v[12:13], v[14:15], 2, v[2:3]
	v_add_u32_e32 v14, 0xfe724000, v5
	v_lshl_add_u64 v[64:65], v[14:15], 2, v[2:3]
	v_add_u32_e32 v14, 0xfe725000, v5
	v_lshl_add_u64 v[66:67], v[14:15], 2, v[2:3]
	v_add_u32_e32 v14, 0xfe726000, v5
	v_lshl_add_u64 v[68:69], v[14:15], 2, v[2:3]
	v_add_u32_e32 v14, 0xfe727000, v5
	global_load_dwordx2 v[6:7], v[6:7], off
	s_nop 0
	global_load_dwordx2 v[8:9], v[8:9], off
	v_lshl_add_u64 v[70:71], v[14:15], 2, v[2:3]
	global_load_dwordx2 v[10:11], v[10:11], off
	s_nop 0
	global_load_dwordx2 v[12:13], v[12:13], off
	s_nop 0
	global_load_dwordx2 v[64:65], v[64:65], off
	s_nop 0
	global_load_dwordx2 v[66:67], v[66:67], off
	s_nop 0
	global_load_dwordx2 v[68:69], v[68:69], off
	s_nop 0
	global_load_dwordx2 v[70:71], v[70:71], off
	s_add_i32 s1, s1, 0x8000
	v_add_u32_e32 v5, s1, v62
	v_add_u32_e32 v14, 0xfe720000, v5
	v_lshl_add_u64 v[150:151], v[14:15], 2, v[2:3]
	v_add_u32_e32 v14, 0xfe721000, v5
	v_lshl_add_u64 v[152:153], v[14:15], 2, v[2:3]
	v_add_u32_e32 v14, 0xfe722000, v5
	v_lshl_add_u64 v[154:155], v[14:15], 2, v[2:3]
	v_add_u32_e32 v14, 0xfe723000, v5
	v_lshl_add_u64 v[156:157], v[14:15], 2, v[2:3]
	v_add_u32_e32 v14, 0xfe724000, v5
	v_lshl_add_u64 v[158:159], v[14:15], 2, v[2:3]
	v_add_u32_e32 v14, 0xfe725000, v5
	v_lshl_add_u64 v[160:161], v[14:15], 2, v[2:3]
	v_add_u32_e32 v14, 0xfe726000, v5
	v_lshl_add_u64 v[162:163], v[14:15], 2, v[2:3]
	v_add_u32_e32 v14, 0xfe727000, v5
	global_load_dwordx2 v[150:151], v[150:151], off
	s_nop 0
	global_load_dwordx2 v[152:153], v[152:153], off
	v_lshl_add_u64 v[164:165], v[14:15], 2, v[2:3]
	global_load_dwordx2 v[154:155], v[154:155], off
	s_nop 0
	global_load_dwordx2 v[156:157], v[156:157], off
	s_nop 0
	global_load_dwordx2 v[158:159], v[158:159], off
	s_nop 0
	global_load_dwordx2 v[160:161], v[160:161], off
	s_nop 0
	global_load_dwordx2 v[162:163], v[162:163], off
	s_nop 0
	global_load_dwordx2 v[164:165], v[164:165], off
	s_add_i32 s1, s1, 0x8000
	v_add_u32_e32 v5, s1, v62
	v_add_u32_e32 v14, 0xfe720000, v5
	v_lshl_add_u64 v[166:167], v[14:15], 2, v[2:3]
	v_add_u32_e32 v14, 0xfe721000, v5
	v_lshl_add_u64 v[168:169], v[14:15], 2, v[2:3]
	v_add_u32_e32 v14, 0xfe722000, v5
	v_lshl_add_u64 v[170:171], v[14:15], 2, v[2:3]
	v_add_u32_e32 v14, 0xfe723000, v5
	v_lshl_add_u64 v[172:173], v[14:15], 2, v[2:3]
	v_add_u32_e32 v14, 0xfe724000, v5
	v_lshl_add_u64 v[174:175], v[14:15], 2, v[2:3]
	v_add_u32_e32 v14, 0xfe725000, v5
	v_lshl_add_u64 v[176:177], v[14:15], 2, v[2:3]
	v_add_u32_e32 v14, 0xfe726000, v5
	v_lshl_add_u64 v[178:179], v[14:15], 2, v[2:3]
	v_add_u32_e32 v14, 0xfe727000, v5
	global_load_dwordx2 v[166:167], v[166:167], off
	s_nop 0
	global_load_dwordx2 v[168:169], v[168:169], off
	v_lshl_add_u64 v[180:181], v[14:15], 2, v[2:3]
	global_load_dwordx2 v[170:171], v[170:171], off
	s_nop 0
	global_load_dwordx2 v[172:173], v[172:173], off
	s_nop 0
	global_load_dwordx2 v[174:175], v[174:175], off
	s_nop 0
	global_load_dwordx2 v[176:177], v[176:177], off
	s_nop 0
	global_load_dwordx2 v[178:179], v[178:179], off
	s_nop 0
	global_load_dwordx2 v[180:181], v[180:181], off
	s_add_i32 s1, s1, 0x8000
	v_add_u32_e32 v5, s1, v62
	v_add_u32_e32 v14, 0xfe720000, v5
	v_lshl_add_u64 v[182:183], v[14:15], 2, v[2:3]
	v_add_u32_e32 v14, 0xfe721000, v5
	v_lshl_add_u64 v[184:185], v[14:15], 2, v[2:3]
	v_add_u32_e32 v14, 0xfe722000, v5
	v_lshl_add_u64 v[186:187], v[14:15], 2, v[2:3]
	v_add_u32_e32 v14, 0xfe723000, v5
	v_lshl_add_u64 v[188:189], v[14:15], 2, v[2:3]
	v_add_u32_e32 v14, 0xfe724000, v5
	v_lshl_add_u64 v[190:191], v[14:15], 2, v[2:3]
	v_add_u32_e32 v14, 0xfe725000, v5
	v_lshl_add_u64 v[192:193], v[14:15], 2, v[2:3]
	v_add_u32_e32 v14, 0xfe726000, v5
	v_lshl_add_u64 v[194:195], v[14:15], 2, v[2:3]
	v_add_u32_e32 v14, 0xfe727000, v5
	global_load_dwordx2 v[182:183], v[182:183], off
	s_nop 0
	global_load_dwordx2 v[184:185], v[184:185], off
	v_lshl_add_u64 v[196:197], v[14:15], 2, v[2:3]
	global_load_dwordx2 v[186:187], v[186:187], off
	s_nop 0
	global_load_dwordx2 v[188:189], v[188:189], off
	s_nop 0
	global_load_dwordx2 v[190:191], v[190:191], off
	s_nop 0
	global_load_dwordx2 v[192:193], v[192:193], off
	s_nop 0
	global_load_dwordx2 v[194:195], v[194:195], off
	s_nop 0
	global_load_dwordx2 v[196:197], v[196:197], off
	s_add_i32 s1, s1, 0x8000
	v_add_u32_e32 v5, 0x410, v4
	v_add_u32_e32 v14, 0x618, v4
	v_add_u32_e32 v63, 0x820, v4
	v_add_u32_e32 v72, 0xa28, v4
	v_add_u32_e32 v73, 0xc30, v4
	v_add_u32_e32 v74, 0xe38, v4
	s_waitcnt vmcnt(31)
	ds_write2_b32 v4, v6, v7 offset1:1
	s_waitcnt vmcnt(30)
	ds_write2_b32 v4, v8, v9 offset0:130 offset1:131
	v_add_u32_e32 v4, 0x1040, v4
	s_waitcnt vmcnt(29)
	ds_write2_b32 v5, v10, v11 offset1:1
	s_waitcnt vmcnt(28)
	ds_write2_b32 v14, v12, v13 offset1:1
	s_waitcnt vmcnt(27)
	ds_write2_b32 v63, v64, v65 offset1:1
	s_waitcnt vmcnt(26)
	ds_write2_b32 v72, v66, v67 offset1:1
	s_waitcnt vmcnt(25)
	ds_write2_b32 v73, v68, v69 offset1:1
	s_waitcnt vmcnt(24)
	ds_write2_b32 v74, v70, v71 offset1:1
	v_add_u32_e32 v5, 0x410, v4
	v_add_u32_e32 v14, 0x618, v4
	v_add_u32_e32 v63, 0x820, v4
	v_add_u32_e32 v72, 0xa28, v4
	v_add_u32_e32 v73, 0xc30, v4
	v_add_u32_e32 v74, 0xe38, v4
	s_waitcnt vmcnt(23)
	ds_write2_b32 v4, v150, v151 offset1:1
	s_waitcnt vmcnt(22)
	ds_write2_b32 v4, v152, v153 offset0:130 offset1:131
	v_add_u32_e32 v4, 0x1040, v4
	s_waitcnt vmcnt(21)
	ds_write2_b32 v5, v154, v155 offset1:1
	s_waitcnt vmcnt(20)
	ds_write2_b32 v14, v156, v157 offset1:1
	s_waitcnt vmcnt(19)
	ds_write2_b32 v63, v158, v159 offset1:1
	s_waitcnt vmcnt(18)
	ds_write2_b32 v72, v160, v161 offset1:1
	s_waitcnt vmcnt(17)
	ds_write2_b32 v73, v162, v163 offset1:1
	s_waitcnt vmcnt(16)
	ds_write2_b32 v74, v164, v165 offset1:1
	v_add_u32_e32 v5, 0x410, v4
	v_add_u32_e32 v14, 0x618, v4
	v_add_u32_e32 v63, 0x820, v4
	v_add_u32_e32 v72, 0xa28, v4
	v_add_u32_e32 v73, 0xc30, v4
	v_add_u32_e32 v74, 0xe38, v4
	s_waitcnt vmcnt(15)
	ds_write2_b32 v4, v166, v167 offset1:1
	s_waitcnt vmcnt(14)
	ds_write2_b32 v4, v168, v169 offset0:130 offset1:131
	v_add_u32_e32 v4, 0x1040, v4
	s_waitcnt vmcnt(13)
	ds_write2_b32 v5, v170, v171 offset1:1
	s_waitcnt vmcnt(12)
	ds_write2_b32 v14, v172, v173 offset1:1
	s_waitcnt vmcnt(11)
	ds_write2_b32 v63, v174, v175 offset1:1
	s_waitcnt vmcnt(10)
	ds_write2_b32 v72, v176, v177 offset1:1
	s_waitcnt vmcnt(9)
	ds_write2_b32 v73, v178, v179 offset1:1
	s_waitcnt vmcnt(8)
	ds_write2_b32 v74, v180, v181 offset1:1
	v_add_u32_e32 v5, 0x410, v4
	v_add_u32_e32 v14, 0x618, v4
	v_add_u32_e32 v63, 0x820, v4
	v_add_u32_e32 v72, 0xa28, v4
	v_add_u32_e32 v73, 0xc30, v4
	v_add_u32_e32 v74, 0xe38, v4
	s_waitcnt vmcnt(7)
	ds_write2_b32 v4, v182, v183 offset1:1
	s_waitcnt vmcnt(6)
	ds_write2_b32 v4, v184, v185 offset0:130 offset1:131
	v_add_u32_e32 v4, 0x1040, v4
	s_waitcnt vmcnt(5)
	ds_write2_b32 v5, v186, v187 offset1:1
	s_waitcnt vmcnt(4)
	ds_write2_b32 v14, v188, v189 offset1:1
	s_waitcnt vmcnt(3)
	ds_write2_b32 v63, v190, v191 offset1:1
	s_waitcnt vmcnt(2)
	ds_write2_b32 v72, v192, v193 offset1:1
	s_waitcnt vmcnt(1)
	ds_write2_b32 v73, v194, v195 offset1:1
	s_waitcnt vmcnt(0)
	ds_write2_b32 v74, v196, v197 offset1:1
	s_waitcnt lgkmcnt(0)
	v_add_u32_e32 v12, 0x400, v81
	ds_read2_b32 v[216:217], v81 offset1:65
	ds_read2_b32 v[218:219], v81 offset0:130 offset1:195
	ds_read2_b32 v[220:221], v12 offset0:4 offset1:69
	ds_read2_b32 v[222:223], v12 offset0:134 offset1:199
	ds_read2_b32 v[224:225], v81 offset0:8 offset1:73
	ds_read2_b32 v[226:227], v81 offset0:138 offset1:203
	ds_read2_b32 v[228:229], v12 offset0:12 offset1:77
	s_waitcnt lgkmcnt(6)
	v_cvt_pk_bf16_f32 v2, v216, v217
	ds_read2_b32 v[230:231], v12 offset0:142 offset1:207
	s_lshl_b32 s1, s96, 1
	s_waitcnt lgkmcnt(6)
	v_cvt_pk_bf16_f32 v3, v218, v219
	ds_read2_b32 v[216:217], v81 offset0:16 offset1:81
	s_and_b32 s1, s1, 0x3fc0
	s_waitcnt lgkmcnt(6)
	v_cvt_pk_bf16_f32 v4, v220, v221
	v_or_b32_e32 v5, s0, v80
	s_add_i32 s8, s1, 0xffffce40
	v_lshlrev_b32_e32 v14, 11, v5
	v_lshl_add_u64 v[8:9], s[8:9], 1, v[32:33]
	ds_read2_b32 v[218:219], v81 offset0:146 offset1:211
	s_waitcnt lgkmcnt(6)
	v_cvt_pk_bf16_f32 v5, v222, v223
	v_lshl_add_u64 v[10:11], v[8:9], 0, v[14:15]
	ds_read2_b32 v[220:221], v12 offset0:20 offset1:85
	global_store_dwordx4 v[10:11], v[2:5], off
	v_or_b32_e32 v10, s0, v82
	v_lshlrev_b32_e32 v14, 11, v10
	s_waitcnt lgkmcnt(6)
	v_cvt_pk_bf16_f32 v2, v224, v225
	ds_read2_b32 v[222:223], v12 offset0:150 offset1:215
	s_waitcnt lgkmcnt(6)
	v_cvt_pk_bf16_f32 v3, v226, v227
	ds_read2_b32 v[224:225], v81 offset0:24 offset1:89
	s_waitcnt lgkmcnt(6)
	v_cvt_pk_bf16_f32 v4, v228, v229
	ds_read2_b32 v[226:227], v81 offset0:154 offset1:219
	s_waitcnt lgkmcnt(6)
	v_cvt_pk_bf16_f32 v5, v230, v231
	v_lshl_add_u64 v[10:11], v[8:9], 0, v[14:15]
	ds_read2_b32 v[228:229], v12 offset0:28 offset1:93
	global_store_dwordx4 v[10:11], v[2:5], off
	v_or_b32_e32 v10, s0, v83
	v_lshlrev_b32_e32 v14, 11, v10
	s_waitcnt lgkmcnt(6)
	v_cvt_pk_bf16_f32 v2, v216, v217
	ds_read2_b32 v[230:231], v12 offset0:158 offset1:223
	s_waitcnt lgkmcnt(6)
	v_cvt_pk_bf16_f32 v3, v218, v219
	ds_read2_b32 v[216:217], v81 offset0:32 offset1:97
	s_waitcnt lgkmcnt(6)
	v_cvt_pk_bf16_f32 v4, v220, v221
	ds_read2_b32 v[218:219], v81 offset0:162 offset1:227
	s_waitcnt lgkmcnt(6)
	v_cvt_pk_bf16_f32 v5, v222, v223
	v_lshl_add_u64 v[10:11], v[8:9], 0, v[14:15]
	ds_read2_b32 v[220:221], v12 offset0:36 offset1:101
	global_store_dwordx4 v[10:11], v[2:5], off
	v_or_b32_e32 v10, s0, v84
	v_lshlrev_b32_e32 v14, 11, v10
	s_waitcnt lgkmcnt(6)
	v_cvt_pk_bf16_f32 v2, v224, v225
	ds_read2_b32 v[222:223], v12 offset0:166 offset1:231
	s_waitcnt lgkmcnt(6)
	v_cvt_pk_bf16_f32 v3, v226, v227
	ds_read2_b32 v[224:225], v81 offset0:40 offset1:105
	s_waitcnt lgkmcnt(6)
	v_cvt_pk_bf16_f32 v4, v228, v229
	ds_read2_b32 v[226:227], v81 offset0:170 offset1:235
	s_waitcnt lgkmcnt(6)
	v_cvt_pk_bf16_f32 v5, v230, v231
	v_lshl_add_u64 v[10:11], v[8:9], 0, v[14:15]
	ds_read2_b32 v[228:229], v12 offset0:44 offset1:109
	global_store_dwordx4 v[10:11], v[2:5], off
	v_or_b32_e32 v10, s0, v85
	v_lshlrev_b32_e32 v14, 11, v10
	s_waitcnt lgkmcnt(6)
	v_cvt_pk_bf16_f32 v2, v216, v217
	ds_read2_b32 v[230:231], v12 offset0:174 offset1:239
	s_waitcnt lgkmcnt(6)
	v_cvt_pk_bf16_f32 v3, v218, v219
	ds_read2_b32 v[216:217], v81 offset0:48 offset1:113
	s_waitcnt lgkmcnt(6)
	v_cvt_pk_bf16_f32 v4, v220, v221
	ds_read2_b32 v[218:219], v81 offset0:178 offset1:243
	s_waitcnt lgkmcnt(6)
	v_cvt_pk_bf16_f32 v5, v222, v223
	v_lshl_add_u64 v[10:11], v[8:9], 0, v[14:15]
	ds_read2_b32 v[220:221], v12 offset0:52 offset1:117
	global_store_dwordx4 v[10:11], v[2:5], off
	v_or_b32_e32 v10, s0, v86
	v_lshlrev_b32_e32 v14, 11, v10
	s_waitcnt lgkmcnt(6)
	v_cvt_pk_bf16_f32 v2, v224, v225
	ds_read2_b32 v[222:223], v12 offset0:182 offset1:247
	s_waitcnt lgkmcnt(6)
	v_cvt_pk_bf16_f32 v3, v226, v227
	ds_read2_b32 v[224:225], v81 offset0:56 offset1:121
	s_waitcnt lgkmcnt(6)
	v_cvt_pk_bf16_f32 v4, v228, v229
	ds_read2_b32 v[226:227], v81 offset0:186 offset1:251
	s_waitcnt lgkmcnt(6)
	v_cvt_pk_bf16_f32 v5, v230, v231
	v_lshl_add_u64 v[10:11], v[8:9], 0, v[14:15]
	ds_read2_b32 v[228:229], v12 offset0:60 offset1:125
	global_store_dwordx4 v[10:11], v[2:5], off
	v_or_b32_e32 v10, s0, v87
	v_lshlrev_b32_e32 v14, 11, v10
	s_waitcnt lgkmcnt(6)
	v_cvt_pk_bf16_f32 v2, v216, v217
	ds_read2_b32 v[230:231], v12 offset0:190 offset1:255
	s_waitcnt lgkmcnt(6)
	v_cvt_pk_bf16_f32 v3, v218, v219
	s_waitcnt lgkmcnt(5)
	v_cvt_pk_bf16_f32 v4, v220, v221
	s_waitcnt lgkmcnt(4)
	v_cvt_pk_bf16_f32 v5, v222, v223
	v_lshl_add_u64 v[10:11], v[8:9], 0, v[14:15]
	global_store_dwordx4 v[10:11], v[2:5], off
	s_nop 0
	s_waitcnt lgkmcnt(3)
	v_cvt_pk_bf16_f32 v2, v224, v225
	s_waitcnt lgkmcnt(2)
	v_cvt_pk_bf16_f32 v3, v226, v227
	s_waitcnt lgkmcnt(1)
	v_cvt_pk_bf16_f32 v4, v228, v229
	v_or_b32_e32 v5, s0, v88
	v_lshlrev_b32_e32 v14, 11, v5
	s_waitcnt lgkmcnt(0)
	v_cvt_pk_bf16_f32 v5, v230, v231
	v_lshl_add_u64 v[6:7], v[8:9], 0, v[14:15]
	global_store_dwordx4 v[6:7], v[2:5], off

.LBB0_60:
	v_add_u32_e32 v5, s1, v62
	v_add_u32_e32 v14, 0xfe920000, v5
	v_lshl_add_u64 v[6:7], v[14:15], 2, v[2:3]
	v_add_u32_e32 v14, 0xfe921000, v5
	v_lshl_add_u64 v[8:9], v[14:15], 2, v[2:3]
	v_add_u32_e32 v14, 0xfe922000, v5
	v_lshl_add_u64 v[10:11], v[14:15], 2, v[2:3]
	v_add_u32_e32 v14, 0xfe923000, v5
	v_lshl_add_u64 v[12:13], v[14:15], 2, v[2:3]
	v_add_u32_e32 v14, 0xfe924000, v5
	v_lshl_add_u64 v[64:65], v[14:15], 2, v[2:3]
	v_add_u32_e32 v14, 0xfe925000, v5
	v_lshl_add_u64 v[66:67], v[14:15], 2, v[2:3]
	v_add_u32_e32 v14, 0xfe926000, v5
	v_lshl_add_u64 v[68:69], v[14:15], 2, v[2:3]
	v_add_u32_e32 v14, 0xfe927000, v5
	global_load_dwordx2 v[6:7], v[6:7], off
	s_nop 0
	global_load_dwordx2 v[8:9], v[8:9], off
	v_lshl_add_u64 v[70:71], v[14:15], 2, v[2:3]
	global_load_dwordx2 v[10:11], v[10:11], off
	s_nop 0
	global_load_dwordx2 v[12:13], v[12:13], off
	s_nop 0
	global_load_dwordx2 v[64:65], v[64:65], off
	s_nop 0
	global_load_dwordx2 v[66:67], v[66:67], off
	s_nop 0
	global_load_dwordx2 v[68:69], v[68:69], off
	s_nop 0
	global_load_dwordx2 v[70:71], v[70:71], off
	s_add_i32 s1, s1, 0x8000
	v_add_u32_e32 v5, s1, v62
	v_add_u32_e32 v14, 0xfe920000, v5
	v_lshl_add_u64 v[150:151], v[14:15], 2, v[2:3]
	v_add_u32_e32 v14, 0xfe921000, v5
	v_lshl_add_u64 v[152:153], v[14:15], 2, v[2:3]
	v_add_u32_e32 v14, 0xfe922000, v5
	v_lshl_add_u64 v[154:155], v[14:15], 2, v[2:3]
	v_add_u32_e32 v14, 0xfe923000, v5
	v_lshl_add_u64 v[156:157], v[14:15], 2, v[2:3]
	v_add_u32_e32 v14, 0xfe924000, v5
	v_lshl_add_u64 v[158:159], v[14:15], 2, v[2:3]
	v_add_u32_e32 v14, 0xfe925000, v5
	v_lshl_add_u64 v[160:161], v[14:15], 2, v[2:3]
	v_add_u32_e32 v14, 0xfe926000, v5
	v_lshl_add_u64 v[162:163], v[14:15], 2, v[2:3]
	v_add_u32_e32 v14, 0xfe927000, v5
	global_load_dwordx2 v[150:151], v[150:151], off
	s_nop 0
	global_load_dwordx2 v[152:153], v[152:153], off
	v_lshl_add_u64 v[164:165], v[14:15], 2, v[2:3]
	global_load_dwordx2 v[154:155], v[154:155], off
	s_nop 0
	global_load_dwordx2 v[156:157], v[156:157], off
	s_nop 0
	global_load_dwordx2 v[158:159], v[158:159], off
	s_nop 0
	global_load_dwordx2 v[160:161], v[160:161], off
	s_nop 0
	global_load_dwordx2 v[162:163], v[162:163], off
	s_nop 0
	global_load_dwordx2 v[164:165], v[164:165], off
	s_add_i32 s1, s1, 0x8000
	v_add_u32_e32 v5, s1, v62
	v_add_u32_e32 v14, 0xfe920000, v5
	v_lshl_add_u64 v[166:167], v[14:15], 2, v[2:3]
	v_add_u32_e32 v14, 0xfe921000, v5
	v_lshl_add_u64 v[168:169], v[14:15], 2, v[2:3]
	v_add_u32_e32 v14, 0xfe922000, v5
	v_lshl_add_u64 v[170:171], v[14:15], 2, v[2:3]
	v_add_u32_e32 v14, 0xfe923000, v5
	v_lshl_add_u64 v[172:173], v[14:15], 2, v[2:3]
	v_add_u32_e32 v14, 0xfe924000, v5
	v_lshl_add_u64 v[174:175], v[14:15], 2, v[2:3]
	v_add_u32_e32 v14, 0xfe925000, v5
	v_lshl_add_u64 v[176:177], v[14:15], 2, v[2:3]
	v_add_u32_e32 v14, 0xfe926000, v5
	v_lshl_add_u64 v[178:179], v[14:15], 2, v[2:3]
	v_add_u32_e32 v14, 0xfe927000, v5
	global_load_dwordx2 v[166:167], v[166:167], off
	s_nop 0
	global_load_dwordx2 v[168:169], v[168:169], off
	v_lshl_add_u64 v[180:181], v[14:15], 2, v[2:3]
	global_load_dwordx2 v[170:171], v[170:171], off
	s_nop 0
	global_load_dwordx2 v[172:173], v[172:173], off
	s_nop 0
	global_load_dwordx2 v[174:175], v[174:175], off
	s_nop 0
	global_load_dwordx2 v[176:177], v[176:177], off
	s_nop 0
	global_load_dwordx2 v[178:179], v[178:179], off
	s_nop 0
	global_load_dwordx2 v[180:181], v[180:181], off
	s_add_i32 s1, s1, 0x8000
	v_add_u32_e32 v5, s1, v62
	v_add_u32_e32 v14, 0xfe920000, v5
	v_lshl_add_u64 v[182:183], v[14:15], 2, v[2:3]
	v_add_u32_e32 v14, 0xfe921000, v5
	v_lshl_add_u64 v[184:185], v[14:15], 2, v[2:3]
	v_add_u32_e32 v14, 0xfe922000, v5
	v_lshl_add_u64 v[186:187], v[14:15], 2, v[2:3]
	v_add_u32_e32 v14, 0xfe923000, v5
	v_lshl_add_u64 v[188:189], v[14:15], 2, v[2:3]
	v_add_u32_e32 v14, 0xfe924000, v5
	v_lshl_add_u64 v[190:191], v[14:15], 2, v[2:3]
	v_add_u32_e32 v14, 0xfe925000, v5
	v_lshl_add_u64 v[192:193], v[14:15], 2, v[2:3]
	v_add_u32_e32 v14, 0xfe926000, v5
	v_lshl_add_u64 v[194:195], v[14:15], 2, v[2:3]
	v_add_u32_e32 v14, 0xfe927000, v5
	global_load_dwordx2 v[182:183], v[182:183], off
	s_nop 0
	global_load_dwordx2 v[184:185], v[184:185], off
	v_lshl_add_u64 v[196:197], v[14:15], 2, v[2:3]
	global_load_dwordx2 v[186:187], v[186:187], off
	s_nop 0
	global_load_dwordx2 v[188:189], v[188:189], off
	s_nop 0
	global_load_dwordx2 v[190:191], v[190:191], off
	s_nop 0
	global_load_dwordx2 v[192:193], v[192:193], off
	s_nop 0
	global_load_dwordx2 v[194:195], v[194:195], off
	s_nop 0
	global_load_dwordx2 v[196:197], v[196:197], off
	s_add_i32 s1, s1, 0x8000
	v_add_u32_e32 v5, 0x410, v4
	v_add_u32_e32 v14, 0x618, v4
	v_add_u32_e32 v63, 0x820, v4
	v_add_u32_e32 v72, 0xa28, v4
	v_add_u32_e32 v73, 0xc30, v4
	v_add_u32_e32 v74, 0xe38, v4
	s_waitcnt vmcnt(31)
	ds_write2_b32 v4, v6, v7 offset1:1
	s_waitcnt vmcnt(30)
	ds_write2_b32 v4, v8, v9 offset0:130 offset1:131
	v_add_u32_e32 v4, 0x1040, v4
	s_waitcnt vmcnt(29)
	ds_write2_b32 v5, v10, v11 offset1:1
	s_waitcnt vmcnt(28)
	ds_write2_b32 v14, v12, v13 offset1:1
	s_waitcnt vmcnt(27)
	ds_write2_b32 v63, v64, v65 offset1:1
	s_waitcnt vmcnt(26)
	ds_write2_b32 v72, v66, v67 offset1:1
	s_waitcnt vmcnt(25)
	ds_write2_b32 v73, v68, v69 offset1:1
	s_waitcnt vmcnt(24)
	ds_write2_b32 v74, v70, v71 offset1:1
	v_add_u32_e32 v5, 0x410, v4
	v_add_u32_e32 v14, 0x618, v4
	v_add_u32_e32 v63, 0x820, v4
	v_add_u32_e32 v72, 0xa28, v4
	v_add_u32_e32 v73, 0xc30, v4
	v_add_u32_e32 v74, 0xe38, v4
	s_waitcnt vmcnt(23)
	ds_write2_b32 v4, v150, v151 offset1:1
	s_waitcnt vmcnt(22)
	ds_write2_b32 v4, v152, v153 offset0:130 offset1:131
	v_add_u32_e32 v4, 0x1040, v4
	s_waitcnt vmcnt(21)
	ds_write2_b32 v5, v154, v155 offset1:1
	s_waitcnt vmcnt(20)
	ds_write2_b32 v14, v156, v157 offset1:1
	s_waitcnt vmcnt(19)
	ds_write2_b32 v63, v158, v159 offset1:1
	s_waitcnt vmcnt(18)
	ds_write2_b32 v72, v160, v161 offset1:1
	s_waitcnt vmcnt(17)
	ds_write2_b32 v73, v162, v163 offset1:1
	s_waitcnt vmcnt(16)
	ds_write2_b32 v74, v164, v165 offset1:1
	v_add_u32_e32 v5, 0x410, v4
	v_add_u32_e32 v14, 0x618, v4
	v_add_u32_e32 v63, 0x820, v4
	v_add_u32_e32 v72, 0xa28, v4
	v_add_u32_e32 v73, 0xc30, v4
	v_add_u32_e32 v74, 0xe38, v4
	s_waitcnt vmcnt(15)
	ds_write2_b32 v4, v166, v167 offset1:1
	s_waitcnt vmcnt(14)
	ds_write2_b32 v4, v168, v169 offset0:130 offset1:131
	v_add_u32_e32 v4, 0x1040, v4
	s_waitcnt vmcnt(13)
	ds_write2_b32 v5, v170, v171 offset1:1
	s_waitcnt vmcnt(12)
	ds_write2_b32 v14, v172, v173 offset1:1
	s_waitcnt vmcnt(11)
	ds_write2_b32 v63, v174, v175 offset1:1
	s_waitcnt vmcnt(10)
	ds_write2_b32 v72, v176, v177 offset1:1
	s_waitcnt vmcnt(9)
	ds_write2_b32 v73, v178, v179 offset1:1
	s_waitcnt vmcnt(8)
	ds_write2_b32 v74, v180, v181 offset1:1
	v_add_u32_e32 v5, 0x410, v4
	v_add_u32_e32 v14, 0x618, v4
	v_add_u32_e32 v63, 0x820, v4
	v_add_u32_e32 v72, 0xa28, v4
	v_add_u32_e32 v73, 0xc30, v4
	v_add_u32_e32 v74, 0xe38, v4
	s_waitcnt vmcnt(7)
	ds_write2_b32 v4, v182, v183 offset1:1
	s_waitcnt vmcnt(6)
	ds_write2_b32 v4, v184, v185 offset0:130 offset1:131
	v_add_u32_e32 v4, 0x1040, v4
	s_waitcnt vmcnt(5)
	ds_write2_b32 v5, v186, v187 offset1:1
	s_waitcnt vmcnt(4)
	ds_write2_b32 v14, v188, v189 offset1:1
	s_waitcnt vmcnt(3)
	ds_write2_b32 v63, v190, v191 offset1:1
	s_waitcnt vmcnt(2)
	ds_write2_b32 v72, v192, v193 offset1:1
	s_waitcnt vmcnt(1)
	ds_write2_b32 v73, v194, v195 offset1:1
	s_waitcnt vmcnt(0)
	ds_write2_b32 v74, v196, v197 offset1:1
	s_waitcnt lgkmcnt(0)
	v_add_u32_e32 v12, 0x400, v81
	ds_read2_b32 v[216:217], v81 offset1:65
	ds_read2_b32 v[218:219], v81 offset0:130 offset1:195
	ds_read2_b32 v[220:221], v12 offset0:4 offset1:69
	ds_read2_b32 v[222:223], v12 offset0:134 offset1:199
	ds_read2_b32 v[224:225], v81 offset0:8 offset1:73
	ds_read2_b32 v[226:227], v81 offset0:138 offset1:203
	ds_read2_b32 v[228:229], v12 offset0:12 offset1:77
	s_waitcnt lgkmcnt(6)
	v_cvt_pk_bf16_f32 v2, v216, v217
	ds_read2_b32 v[230:231], v12 offset0:142 offset1:207
	s_lshl_b32 s1, s96, 1
	s_waitcnt lgkmcnt(6)
	v_cvt_pk_bf16_f32 v3, v218, v219
	ds_read2_b32 v[216:217], v81 offset0:16 offset1:81
	s_and_b32 s1, s1, 0x3fc0
	s_waitcnt lgkmcnt(6)
	v_cvt_pk_bf16_f32 v4, v220, v221
	v_or_b32_e32 v5, s0, v80
	s_add_i32 s8, s1, 0xffffd240
	v_lshlrev_b32_e32 v14, 11, v5
	v_lshl_add_u64 v[8:9], s[8:9], 1, v[36:37]
	ds_read2_b32 v[218:219], v81 offset0:146 offset1:211
	s_waitcnt lgkmcnt(6)
	v_cvt_pk_bf16_f32 v5, v222, v223
	v_lshl_add_u64 v[10:11], v[8:9], 0, v[14:15]
	ds_read2_b32 v[220:221], v12 offset0:20 offset1:85
	global_store_dwordx4 v[10:11], v[2:5], off
	v_or_b32_e32 v10, s0, v82
	v_lshlrev_b32_e32 v14, 11, v10
	s_waitcnt lgkmcnt(6)
	v_cvt_pk_bf16_f32 v2, v224, v225
	ds_read2_b32 v[222:223], v12 offset0:150 offset1:215
	s_waitcnt lgkmcnt(6)
	v_cvt_pk_bf16_f32 v3, v226, v227
	ds_read2_b32 v[224:225], v81 offset0:24 offset1:89
	s_waitcnt lgkmcnt(6)
	v_cvt_pk_bf16_f32 v4, v228, v229
	ds_read2_b32 v[226:227], v81 offset0:154 offset1:219
	s_waitcnt lgkmcnt(6)
	v_cvt_pk_bf16_f32 v5, v230, v231
	v_lshl_add_u64 v[10:11], v[8:9], 0, v[14:15]
	ds_read2_b32 v[228:229], v12 offset0:28 offset1:93
	global_store_dwordx4 v[10:11], v[2:5], off
	v_or_b32_e32 v10, s0, v83
	v_lshlrev_b32_e32 v14, 11, v10
	s_waitcnt lgkmcnt(6)
	v_cvt_pk_bf16_f32 v2, v216, v217
	ds_read2_b32 v[230:231], v12 offset0:158 offset1:223
	s_waitcnt lgkmcnt(6)
	v_cvt_pk_bf16_f32 v3, v218, v219
	ds_read2_b32 v[216:217], v81 offset0:32 offset1:97
	s_waitcnt lgkmcnt(6)
	v_cvt_pk_bf16_f32 v4, v220, v221
	ds_read2_b32 v[218:219], v81 offset0:162 offset1:227
	s_waitcnt lgkmcnt(6)
	v_cvt_pk_bf16_f32 v5, v222, v223
	v_lshl_add_u64 v[10:11], v[8:9], 0, v[14:15]
	ds_read2_b32 v[220:221], v12 offset0:36 offset1:101
	global_store_dwordx4 v[10:11], v[2:5], off
	v_or_b32_e32 v10, s0, v84
	v_lshlrev_b32_e32 v14, 11, v10
	s_waitcnt lgkmcnt(6)
	v_cvt_pk_bf16_f32 v2, v224, v225
	ds_read2_b32 v[222:223], v12 offset0:166 offset1:231
	s_waitcnt lgkmcnt(6)
	v_cvt_pk_bf16_f32 v3, v226, v227
	ds_read2_b32 v[224:225], v81 offset0:40 offset1:105
	s_waitcnt lgkmcnt(6)
	v_cvt_pk_bf16_f32 v4, v228, v229
	ds_read2_b32 v[226:227], v81 offset0:170 offset1:235
	s_waitcnt lgkmcnt(6)
	v_cvt_pk_bf16_f32 v5, v230, v231
	v_lshl_add_u64 v[10:11], v[8:9], 0, v[14:15]
	ds_read2_b32 v[228:229], v12 offset0:44 offset1:109
	global_store_dwordx4 v[10:11], v[2:5], off
	v_or_b32_e32 v10, s0, v85
	v_lshlrev_b32_e32 v14, 11, v10
	s_waitcnt lgkmcnt(6)
	v_cvt_pk_bf16_f32 v2, v216, v217
	ds_read2_b32 v[230:231], v12 offset0:174 offset1:239
	s_waitcnt lgkmcnt(6)
	v_cvt_pk_bf16_f32 v3, v218, v219
	ds_read2_b32 v[216:217], v81 offset0:48 offset1:113
	s_waitcnt lgkmcnt(6)
	v_cvt_pk_bf16_f32 v4, v220, v221
	ds_read2_b32 v[218:219], v81 offset0:178 offset1:243
	s_waitcnt lgkmcnt(6)
	v_cvt_pk_bf16_f32 v5, v222, v223
	v_lshl_add_u64 v[10:11], v[8:9], 0, v[14:15]
	ds_read2_b32 v[220:221], v12 offset0:52 offset1:117
	global_store_dwordx4 v[10:11], v[2:5], off
	v_or_b32_e32 v10, s0, v86
	v_lshlrev_b32_e32 v14, 11, v10
	s_waitcnt lgkmcnt(6)
	v_cvt_pk_bf16_f32 v2, v224, v225
	ds_read2_b32 v[222:223], v12 offset0:182 offset1:247
	s_waitcnt lgkmcnt(6)
	v_cvt_pk_bf16_f32 v3, v226, v227
	ds_read2_b32 v[224:225], v81 offset0:56 offset1:121
	s_waitcnt lgkmcnt(6)
	v_cvt_pk_bf16_f32 v4, v228, v229
	ds_read2_b32 v[226:227], v81 offset0:186 offset1:251
	s_waitcnt lgkmcnt(6)
	v_cvt_pk_bf16_f32 v5, v230, v231
	v_lshl_add_u64 v[10:11], v[8:9], 0, v[14:15]
	ds_read2_b32 v[228:229], v12 offset0:60 offset1:125
	global_store_dwordx4 v[10:11], v[2:5], off
	v_or_b32_e32 v10, s0, v87
	v_lshlrev_b32_e32 v14, 11, v10
	s_waitcnt lgkmcnt(6)
	v_cvt_pk_bf16_f32 v2, v216, v217
	ds_read2_b32 v[230:231], v12 offset0:190 offset1:255
	s_waitcnt lgkmcnt(6)
	v_cvt_pk_bf16_f32 v3, v218, v219
	s_waitcnt lgkmcnt(5)
	v_cvt_pk_bf16_f32 v4, v220, v221
	s_waitcnt lgkmcnt(4)
	v_cvt_pk_bf16_f32 v5, v222, v223
	v_lshl_add_u64 v[10:11], v[8:9], 0, v[14:15]
	global_store_dwordx4 v[10:11], v[2:5], off
	s_nop 0
	s_waitcnt lgkmcnt(3)
	v_cvt_pk_bf16_f32 v2, v224, v225
	s_waitcnt lgkmcnt(2)
	v_cvt_pk_bf16_f32 v3, v226, v227
	s_waitcnt lgkmcnt(1)
	v_cvt_pk_bf16_f32 v4, v228, v229
	v_or_b32_e32 v5, s0, v88
	v_lshlrev_b32_e32 v14, 11, v5
	s_waitcnt lgkmcnt(0)
	v_cvt_pk_bf16_f32 v5, v230, v231
	v_lshl_add_u64 v[6:7], v[8:9], 0, v[14:15]
	global_store_dwordx4 v[6:7], v[2:5], off

.LBB0_82:
	s_waitcnt lgkmcnt(0)
	v_add_u32_e32 v12, 0x400, v81
	ds_read2_b32 v[216:217], v81 offset1:65
	ds_read2_b32 v[218:219], v81 offset0:130 offset1:195
	ds_read2_b32 v[220:221], v12 offset0:4 offset1:69
	ds_read2_b32 v[222:223], v12 offset0:134 offset1:199
	ds_read2_b32 v[224:225], v81 offset0:8 offset1:73
	ds_read2_b32 v[226:227], v81 offset0:138 offset1:203
	ds_read2_b32 v[228:229], v12 offset0:12 offset1:77
	s_waitcnt lgkmcnt(6)
	v_cvt_pk_bf16_f32 v2, v216, v217
	ds_read2_b32 v[230:231], v12 offset0:142 offset1:207
	s_lshl_b32 s1, s96, 1
	s_waitcnt lgkmcnt(6)
	v_cvt_pk_bf16_f32 v3, v218, v219
	ds_read2_b32 v[216:217], v81 offset0:16 offset1:81
	s_and_b32 s1, s1, 0x3fc0
	s_waitcnt lgkmcnt(6)
	v_cvt_pk_bf16_f32 v4, v220, v221
	v_or_b32_e32 v5, s0, v80
	s_add_i32 s8, s1, 0xffffd340
	v_lshlrev_b32_e32 v14, 9, v5
	v_lshl_add_u64 v[8:9], s[8:9], 1, v[40:41]
	ds_read2_b32 v[218:219], v81 offset0:146 offset1:211
	s_waitcnt lgkmcnt(6)
	v_cvt_pk_bf16_f32 v5, v222, v223
	v_lshl_add_u64 v[10:11], v[8:9], 0, v[14:15]
	ds_read2_b32 v[220:221], v12 offset0:20 offset1:85
	global_store_dwordx4 v[10:11], v[2:5], off
	v_or_b32_e32 v10, s0, v82
	v_lshlrev_b32_e32 v14, 9, v10
	s_waitcnt lgkmcnt(6)
	v_cvt_pk_bf16_f32 v2, v224, v225
	ds_read2_b32 v[222:223], v12 offset0:150 offset1:215
	s_waitcnt lgkmcnt(6)
	v_cvt_pk_bf16_f32 v3, v226, v227
	ds_read2_b32 v[224:225], v81 offset0:24 offset1:89
	s_waitcnt lgkmcnt(6)
	v_cvt_pk_bf16_f32 v4, v228, v229
	ds_read2_b32 v[226:227], v81 offset0:154 offset1:219
	s_waitcnt lgkmcnt(6)
	v_cvt_pk_bf16_f32 v5, v230, v231
	v_lshl_add_u64 v[10:11], v[8:9], 0, v[14:15]
	ds_read2_b32 v[228:229], v12 offset0:28 offset1:93
	global_store_dwordx4 v[10:11], v[2:5], off
	v_or_b32_e32 v10, s0, v83
	v_lshlrev_b32_e32 v14, 9, v10
	s_waitcnt lgkmcnt(6)
	v_cvt_pk_bf16_f32 v2, v216, v217
	ds_read2_b32 v[230:231], v12 offset0:158 offset1:223
	s_waitcnt lgkmcnt(6)
	v_cvt_pk_bf16_f32 v3, v218, v219
	ds_read2_b32 v[216:217], v81 offset0:32 offset1:97
	s_waitcnt lgkmcnt(6)
	v_cvt_pk_bf16_f32 v4, v220, v221
	ds_read2_b32 v[218:219], v81 offset0:162 offset1:227
	s_waitcnt lgkmcnt(6)
	v_cvt_pk_bf16_f32 v5, v222, v223
	v_lshl_add_u64 v[10:11], v[8:9], 0, v[14:15]
	ds_read2_b32 v[220:221], v12 offset0:36 offset1:101
	global_store_dwordx4 v[10:11], v[2:5], off
	v_or_b32_e32 v10, s0, v84
	v_lshlrev_b32_e32 v14, 9, v10
	s_waitcnt lgkmcnt(6)
	v_cvt_pk_bf16_f32 v2, v224, v225
	ds_read2_b32 v[222:223], v12 offset0:166 offset1:231
	s_waitcnt lgkmcnt(6)
	v_cvt_pk_bf16_f32 v3, v226, v227
	ds_read2_b32 v[224:225], v81 offset0:40 offset1:105
	s_waitcnt lgkmcnt(6)
	v_cvt_pk_bf16_f32 v4, v228, v229
	ds_read2_b32 v[226:227], v81 offset0:170 offset1:235
	s_waitcnt lgkmcnt(6)
	v_cvt_pk_bf16_f32 v5, v230, v231
	v_lshl_add_u64 v[10:11], v[8:9], 0, v[14:15]
	ds_read2_b32 v[228:229], v12 offset0:44 offset1:109
	global_store_dwordx4 v[10:11], v[2:5], off
	v_or_b32_e32 v10, s0, v85
	v_lshlrev_b32_e32 v14, 9, v10
	s_waitcnt lgkmcnt(6)
	v_cvt_pk_bf16_f32 v2, v216, v217
	ds_read2_b32 v[230:231], v12 offset0:174 offset1:239
	s_waitcnt lgkmcnt(6)
	v_cvt_pk_bf16_f32 v3, v218, v219
	ds_read2_b32 v[216:217], v81 offset0:48 offset1:113
	s_waitcnt lgkmcnt(6)
	v_cvt_pk_bf16_f32 v4, v220, v221
	ds_read2_b32 v[218:219], v81 offset0:178 offset1:243
	s_waitcnt lgkmcnt(6)
	v_cvt_pk_bf16_f32 v5, v222, v223
	v_lshl_add_u64 v[10:11], v[8:9], 0, v[14:15]
	ds_read2_b32 v[220:221], v12 offset0:52 offset1:117
	global_store_dwordx4 v[10:11], v[2:5], off
	v_or_b32_e32 v10, s0, v86
	v_lshlrev_b32_e32 v14, 9, v10
	s_waitcnt lgkmcnt(6)
	v_cvt_pk_bf16_f32 v2, v224, v225
	ds_read2_b32 v[222:223], v12 offset0:182 offset1:247
	s_waitcnt lgkmcnt(6)
	v_cvt_pk_bf16_f32 v3, v226, v227
	ds_read2_b32 v[224:225], v81 offset0:56 offset1:121
	s_waitcnt lgkmcnt(6)
	v_cvt_pk_bf16_f32 v4, v228, v229
	ds_read2_b32 v[226:227], v81 offset0:186 offset1:251
	s_waitcnt lgkmcnt(6)
	v_cvt_pk_bf16_f32 v5, v230, v231
	v_lshl_add_u64 v[10:11], v[8:9], 0, v[14:15]
	ds_read2_b32 v[228:229], v12 offset0:60 offset1:125
	global_store_dwordx4 v[10:11], v[2:5], off
	v_or_b32_e32 v10, s0, v87
	v_lshlrev_b32_e32 v14, 9, v10
	s_waitcnt lgkmcnt(6)
	v_cvt_pk_bf16_f32 v2, v216, v217
	ds_read2_b32 v[230:231], v12 offset0:190 offset1:255
	s_waitcnt lgkmcnt(6)
	v_cvt_pk_bf16_f32 v3, v218, v219
	s_waitcnt lgkmcnt(5)
	v_cvt_pk_bf16_f32 v4, v220, v221
	s_waitcnt lgkmcnt(4)
	v_cvt_pk_bf16_f32 v5, v222, v223
	v_lshl_add_u64 v[10:11], v[8:9], 0, v[14:15]
	global_store_dwordx4 v[10:11], v[2:5], off
	s_nop 0
	s_waitcnt lgkmcnt(3)
	v_cvt_pk_bf16_f32 v2, v224, v225
	s_waitcnt lgkmcnt(2)
	v_cvt_pk_bf16_f32 v3, v226, v227
	s_waitcnt lgkmcnt(1)
	v_cvt_pk_bf16_f32 v4, v228, v229
	v_or_b32_e32 v5, s0, v88
	v_lshlrev_b32_e32 v14, 9, v5
	s_waitcnt lgkmcnt(0)
	v_cvt_pk_bf16_f32 v5, v230, v231
	v_lshl_add_u64 v[6:7], v[8:9], 0, v[14:15]
	global_store_dwordx4 v[6:7], v[2:5], off

.LBB0_103:
	s_waitcnt lgkmcnt(0)
	v_add_u32_e32 v12, 0x400, v81
	ds_read2_b32 v[216:217], v81 offset1:65
	ds_read2_b32 v[218:219], v81 offset0:130 offset1:195
	ds_read2_b32 v[220:221], v12 offset0:4 offset1:69
	ds_read2_b32 v[222:223], v12 offset0:134 offset1:199
	ds_read2_b32 v[224:225], v81 offset0:8 offset1:73
	ds_read2_b32 v[226:227], v81 offset0:138 offset1:203
	ds_read2_b32 v[228:229], v12 offset0:12 offset1:77
	s_waitcnt lgkmcnt(6)
	v_cvt_pk_bf16_f32 v2, v216, v217
	ds_read2_b32 v[230:231], v12 offset0:142 offset1:207
	s_lshl_b32 s8, s5, 1
	v_or_b32_e32 v10, s4, v80
	s_waitcnt lgkmcnt(6)
	v_cvt_pk_bf16_f32 v3, v218, v219
	ds_read2_b32 v[216:217], v81 offset0:16 offset1:81
	v_lshl_add_u64 v[8:9], v[42:43], 0, s[8:9]
	v_lshlrev_b32_e32 v14, 10, v10
	s_waitcnt lgkmcnt(6)
	v_cvt_pk_bf16_f32 v4, v220, v221
	ds_read2_b32 v[218:219], v81 offset0:146 offset1:211
	s_waitcnt lgkmcnt(6)
	v_cvt_pk_bf16_f32 v5, v222, v223
	v_lshl_add_u64 v[10:11], v[8:9], 0, v[14:15]
	ds_read2_b32 v[220:221], v12 offset0:20 offset1:85
	global_store_dwordx4 v[10:11], v[2:5], off
	v_or_b32_e32 v10, s4, v82
	v_lshlrev_b32_e32 v14, 10, v10
	s_waitcnt lgkmcnt(6)
	v_cvt_pk_bf16_f32 v2, v224, v225
	ds_read2_b32 v[222:223], v12 offset0:150 offset1:215
	s_waitcnt lgkmcnt(6)
	v_cvt_pk_bf16_f32 v3, v226, v227
	ds_read2_b32 v[224:225], v81 offset0:24 offset1:89
	s_waitcnt lgkmcnt(6)
	v_cvt_pk_bf16_f32 v4, v228, v229
	ds_read2_b32 v[226:227], v81 offset0:154 offset1:219
	s_waitcnt lgkmcnt(6)
	v_cvt_pk_bf16_f32 v5, v230, v231
	v_lshl_add_u64 v[10:11], v[8:9], 0, v[14:15]
	ds_read2_b32 v[228:229], v12 offset0:28 offset1:93
	global_store_dwordx4 v[10:11], v[2:5], off
	v_or_b32_e32 v10, s4, v83
	v_lshlrev_b32_e32 v14, 10, v10
	s_waitcnt lgkmcnt(6)
	v_cvt_pk_bf16_f32 v2, v216, v217
	ds_read2_b32 v[230:231], v12 offset0:158 offset1:223
	s_waitcnt lgkmcnt(6)
	v_cvt_pk_bf16_f32 v3, v218, v219
	ds_read2_b32 v[216:217], v81 offset0:32 offset1:97
	s_waitcnt lgkmcnt(6)
	v_cvt_pk_bf16_f32 v4, v220, v221
	ds_read2_b32 v[218:219], v81 offset0:162 offset1:227
	s_waitcnt lgkmcnt(6)
	v_cvt_pk_bf16_f32 v5, v222, v223
	v_lshl_add_u64 v[10:11], v[8:9], 0, v[14:15]
	ds_read2_b32 v[220:221], v12 offset0:36 offset1:101
	global_store_dwordx4 v[10:11], v[2:5], off
	v_or_b32_e32 v10, s4, v84
	v_lshlrev_b32_e32 v14, 10, v10
	s_waitcnt lgkmcnt(6)
	v_cvt_pk_bf16_f32 v2, v224, v225
	ds_read2_b32 v[222:223], v12 offset0:166 offset1:231
	s_waitcnt lgkmcnt(6)
	v_cvt_pk_bf16_f32 v3, v226, v227
	ds_read2_b32 v[224:225], v81 offset0:40 offset1:105
	s_waitcnt lgkmcnt(6)
	v_cvt_pk_bf16_f32 v4, v228, v229
	ds_read2_b32 v[226:227], v81 offset0:170 offset1:235
	s_waitcnt lgkmcnt(6)
	v_cvt_pk_bf16_f32 v5, v230, v231
	v_lshl_add_u64 v[10:11], v[8:9], 0, v[14:15]
	ds_read2_b32 v[228:229], v12 offset0:44 offset1:109
	global_store_dwordx4 v[10:11], v[2:5], off
	v_or_b32_e32 v10, s4, v85
	v_lshlrev_b32_e32 v14, 10, v10
	s_waitcnt lgkmcnt(6)
	v_cvt_pk_bf16_f32 v2, v216, v217
	ds_read2_b32 v[230:231], v12 offset0:174 offset1:239
	s_waitcnt lgkmcnt(6)
	v_cvt_pk_bf16_f32 v3, v218, v219
	ds_read2_b32 v[216:217], v81 offset0:48 offset1:113
	s_waitcnt lgkmcnt(6)
	v_cvt_pk_bf16_f32 v4, v220, v221
	ds_read2_b32 v[218:219], v81 offset0:178 offset1:243
	s_waitcnt lgkmcnt(6)
	v_cvt_pk_bf16_f32 v5, v222, v223
	v_lshl_add_u64 v[10:11], v[8:9], 0, v[14:15]
	ds_read2_b32 v[220:221], v12 offset0:52 offset1:117
	global_store_dwordx4 v[10:11], v[2:5], off
	v_or_b32_e32 v10, s4, v86
	v_lshlrev_b32_e32 v14, 10, v10
	s_waitcnt lgkmcnt(6)
	v_cvt_pk_bf16_f32 v2, v224, v225
	ds_read2_b32 v[222:223], v12 offset0:182 offset1:247
	s_waitcnt lgkmcnt(6)
	v_cvt_pk_bf16_f32 v3, v226, v227
	ds_read2_b32 v[224:225], v81 offset0:56 offset1:121
	s_waitcnt lgkmcnt(6)
	v_cvt_pk_bf16_f32 v4, v228, v229
	ds_read2_b32 v[226:227], v81 offset0:186 offset1:251
	s_waitcnt lgkmcnt(6)
	v_cvt_pk_bf16_f32 v5, v230, v231
	v_lshl_add_u64 v[10:11], v[8:9], 0, v[14:15]
	ds_read2_b32 v[228:229], v12 offset0:60 offset1:125
	global_store_dwordx4 v[10:11], v[2:5], off
	v_or_b32_e32 v10, s4, v87
	v_lshlrev_b32_e32 v14, 10, v10
	s_waitcnt lgkmcnt(6)
	v_cvt_pk_bf16_f32 v2, v216, v217
	ds_read2_b32 v[230:231], v12 offset0:190 offset1:255
	s_waitcnt lgkmcnt(6)
	v_cvt_pk_bf16_f32 v3, v218, v219
	s_waitcnt lgkmcnt(5)
	v_cvt_pk_bf16_f32 v4, v220, v221
	s_waitcnt lgkmcnt(4)
	v_cvt_pk_bf16_f32 v5, v222, v223
	v_lshl_add_u64 v[10:11], v[8:9], 0, v[14:15]
	global_store_dwordx4 v[10:11], v[2:5], off
	s_nop 0
	s_waitcnt lgkmcnt(3)
	v_cvt_pk_bf16_f32 v2, v224, v225
	s_waitcnt lgkmcnt(2)
	v_cvt_pk_bf16_f32 v3, v226, v227
	s_waitcnt lgkmcnt(1)
	v_cvt_pk_bf16_f32 v4, v228, v229
	v_or_b32_e32 v5, s4, v88
	v_lshlrev_b32_e32 v14, 10, v5
	s_waitcnt lgkmcnt(0)
	v_cvt_pk_bf16_f32 v5, v230, v231
	v_lshl_add_u64 v[6:7], v[8:9], 0, v[14:15]
	global_store_dwordx4 v[6:7], v[2:5], off

.LBB0_107:
	v_lshl_add_u64 v[64:65], v[10:11], 0, s[0:1]
	v_add_co_u32_e32 v74, vcc, 0xf000, v64
	v_lshl_add_u64 v[62:63], v[12:13], 0, s[0:1]
	s_nop 0
	v_addc_co_u32_e32 v75, vcc, 0, v65, vcc
	v_add_co_u32_e32 v76, vcc, 0x1f000, v64
	v_lshl_add_u64 v[66:67], v[8:9], 0, s[0:1]
	s_nop 0
	v_addc_co_u32_e32 v77, vcc, 0, v65, vcc
	v_lshl_add_u64 v[68:69], v[6:7], 0, s[0:1]
	v_lshl_add_u64 v[70:71], v[4:5], 0, s[0:1]
	v_lshl_add_u64 v[72:73], v[2:3], 0, s[0:1]
	v_add_co_u32_e32 v64, vcc, 0x2e000, v64
	global_load_dwordx2 v[62:63], v[62:63], off
	s_nop 0
	global_load_dwordx2 v[66:67], v[66:67], off
	s_nop 0
	global_load_dwordx2 v[68:69], v[68:69], off
	s_nop 0
	global_load_dwordx2 v[70:71], v[70:71], off
	s_nop 0
	global_load_dwordx2 v[72:73], v[72:73], off
	v_addc_co_u32_e32 v65, vcc, 0, v65, vcc
	global_load_dwordx2 v[74:75], v[74:75], off offset:2560
	s_nop 0
	global_load_dwordx2 v[76:77], v[76:77], off offset:1024
	s_nop 0
	global_load_dwordx2 v[64:65], v[64:65], off offset:3584
	s_add_u32 s0, s0, 0x7d000
	s_addc_u32 s1, s1, 0
	v_lshl_add_u64 v[164:165], v[10:11], 0, s[0:1]
	v_add_co_u32_e32 v160, vcc, 0xf000, v164
	v_lshl_add_u64 v[150:151], v[12:13], 0, s[0:1]
	s_nop 0
	v_addc_co_u32_e32 v161, vcc, 0, v165, vcc
	v_add_co_u32_e32 v162, vcc, 0x1f000, v164
	v_lshl_add_u64 v[152:153], v[8:9], 0, s[0:1]
	s_nop 0
	v_addc_co_u32_e32 v163, vcc, 0, v165, vcc
	v_lshl_add_u64 v[154:155], v[6:7], 0, s[0:1]
	v_lshl_add_u64 v[156:157], v[4:5], 0, s[0:1]
	v_lshl_add_u64 v[158:159], v[2:3], 0, s[0:1]
	v_add_co_u32_e32 v164, vcc, 0x2e000, v164
	global_load_dwordx2 v[150:151], v[150:151], off
	s_nop 0
	global_load_dwordx2 v[152:153], v[152:153], off
	s_nop 0
	global_load_dwordx2 v[154:155], v[154:155], off
	s_nop 0
	global_load_dwordx2 v[156:157], v[156:157], off
	s_nop 0
	global_load_dwordx2 v[158:159], v[158:159], off
	v_addc_co_u32_e32 v165, vcc, 0, v165, vcc
	global_load_dwordx2 v[160:161], v[160:161], off offset:2560
	s_nop 0
	global_load_dwordx2 v[162:163], v[162:163], off offset:1024
	s_nop 0
	global_load_dwordx2 v[164:165], v[164:165], off offset:3584
	s_add_u32 s0, s0, 0x7d000
	s_addc_u32 s1, s1, 0
	v_lshl_add_u64 v[180:181], v[10:11], 0, s[0:1]
	v_add_co_u32_e32 v176, vcc, 0xf000, v180
	v_lshl_add_u64 v[166:167], v[12:13], 0, s[0:1]
	s_nop 0
	v_addc_co_u32_e32 v177, vcc, 0, v181, vcc
	v_add_co_u32_e32 v178, vcc, 0x1f000, v180
	v_lshl_add_u64 v[168:169], v[8:9], 0, s[0:1]
	s_nop 0
	v_addc_co_u32_e32 v179, vcc, 0, v181, vcc
	v_lshl_add_u64 v[170:171], v[6:7], 0, s[0:1]
	v_lshl_add_u64 v[172:173], v[4:5], 0, s[0:1]
	v_lshl_add_u64 v[174:175], v[2:3], 0, s[0:1]
	v_add_co_u32_e32 v180, vcc, 0x2e000, v180
	global_load_dwordx2 v[166:167], v[166:167], off
	s_nop 0
	global_load_dwordx2 v[168:169], v[168:169], off
	s_nop 0
	global_load_dwordx2 v[170:171], v[170:171], off
	s_nop 0
	global_load_dwordx2 v[172:173], v[172:173], off
	s_nop 0
	global_load_dwordx2 v[174:175], v[174:175], off
	v_addc_co_u32_e32 v181, vcc, 0, v181, vcc
	global_load_dwordx2 v[176:177], v[176:177], off offset:2560
	s_nop 0
	global_load_dwordx2 v[178:179], v[178:179], off offset:1024
	s_nop 0
	global_load_dwordx2 v[180:181], v[180:181], off offset:3584
	s_add_u32 s0, s0, 0x7d000
	s_addc_u32 s1, s1, 0
	v_lshl_add_u64 v[196:197], v[10:11], 0, s[0:1]
	v_add_co_u32_e32 v192, vcc, 0xf000, v196
	v_lshl_add_u64 v[182:183], v[12:13], 0, s[0:1]
	s_nop 0
	v_addc_co_u32_e32 v193, vcc, 0, v197, vcc
	v_add_co_u32_e32 v194, vcc, 0x1f000, v196
	v_lshl_add_u64 v[184:185], v[8:9], 0, s[0:1]
	s_nop 0
	v_addc_co_u32_e32 v195, vcc, 0, v197, vcc
	v_lshl_add_u64 v[186:187], v[6:7], 0, s[0:1]
	v_lshl_add_u64 v[188:189], v[4:5], 0, s[0:1]
	v_lshl_add_u64 v[190:191], v[2:3], 0, s[0:1]
	v_add_co_u32_e32 v196, vcc, 0x2e000, v196
	global_load_dwordx2 v[182:183], v[182:183], off
	s_nop 0
	global_load_dwordx2 v[184:185], v[184:185], off
	s_nop 0
	global_load_dwordx2 v[186:187], v[186:187], off
	s_nop 0
	global_load_dwordx2 v[188:189], v[188:189], off
	s_nop 0
	global_load_dwordx2 v[190:191], v[190:191], off
	v_addc_co_u32_e32 v197, vcc, 0, v197, vcc
	global_load_dwordx2 v[192:193], v[192:193], off offset:2560
	s_nop 0
	global_load_dwordx2 v[194:195], v[194:195], off offset:1024
	s_nop 0
	global_load_dwordx2 v[196:197], v[196:197], off offset:3584
	s_add_u32 s0, s0, 0x7d000
	s_addc_u32 s1, s1, 0
	v_add_u32_e32 v108, 0x410, v14
	v_add_u32_e32 v109, 0x618, v14
	v_add_u32_e32 v110, 0x820, v14
	v_add_u32_e32 v111, 0xa28, v14
	v_add_u32_e32 v112, 0xc30, v14
	v_add_u32_e32 v113, 0xe38, v14
	s_waitcnt vmcnt(31)
	ds_write2_b32 v14, v62, v63 offset1:1
	s_waitcnt vmcnt(30)
	ds_write2_b32 v110, v66, v67 offset1:1
	s_waitcnt vmcnt(29)
	ds_write2_b32 v111, v68, v69 offset1:1
	s_waitcnt vmcnt(28)
	ds_write2_b32 v112, v70, v71 offset1:1
	s_waitcnt vmcnt(27)
	ds_write2_b32 v113, v72, v73 offset1:1
	s_waitcnt vmcnt(26)
	ds_write2_b32 v14, v74, v75 offset0:130 offset1:131
	v_add_u32_e32 v14, 0x1040, v14
	s_waitcnt vmcnt(25)
	ds_write2_b32 v108, v76, v77 offset1:1
	s_waitcnt vmcnt(24)
	ds_write2_b32 v109, v64, v65 offset1:1
	v_add_u32_e32 v108, 0x410, v14
	v_add_u32_e32 v109, 0x618, v14
	v_add_u32_e32 v110, 0x820, v14
	v_add_u32_e32 v111, 0xa28, v14
	v_add_u32_e32 v112, 0xc30, v14
	v_add_u32_e32 v113, 0xe38, v14
	s_waitcnt vmcnt(23)
	ds_write2_b32 v14, v150, v151 offset1:1
	s_waitcnt vmcnt(22)
	ds_write2_b32 v110, v152, v153 offset1:1
	s_waitcnt vmcnt(21)
	ds_write2_b32 v111, v154, v155 offset1:1
	s_waitcnt vmcnt(20)
	ds_write2_b32 v112, v156, v157 offset1:1
	s_waitcnt vmcnt(19)
	ds_write2_b32 v113, v158, v159 offset1:1
	s_waitcnt vmcnt(18)
	ds_write2_b32 v14, v160, v161 offset0:130 offset1:131
	v_add_u32_e32 v14, 0x1040, v14
	s_waitcnt vmcnt(17)
	ds_write2_b32 v108, v162, v163 offset1:1
	s_waitcnt vmcnt(16)
	ds_write2_b32 v109, v164, v165 offset1:1
	v_add_u32_e32 v108, 0x410, v14
	v_add_u32_e32 v109, 0x618, v14
	v_add_u32_e32 v110, 0x820, v14
	v_add_u32_e32 v111, 0xa28, v14
	v_add_u32_e32 v112, 0xc30, v14
	v_add_u32_e32 v113, 0xe38, v14
	s_waitcnt vmcnt(15)
	ds_write2_b32 v14, v166, v167 offset1:1
	s_waitcnt vmcnt(14)
	ds_write2_b32 v110, v168, v169 offset1:1
	s_waitcnt vmcnt(13)
	ds_write2_b32 v111, v170, v171 offset1:1
	s_waitcnt vmcnt(12)
	ds_write2_b32 v112, v172, v173 offset1:1
	s_waitcnt vmcnt(11)
	ds_write2_b32 v113, v174, v175 offset1:1
	s_waitcnt vmcnt(10)
	ds_write2_b32 v14, v176, v177 offset0:130 offset1:131
	v_add_u32_e32 v14, 0x1040, v14
	s_waitcnt vmcnt(9)
	ds_write2_b32 v108, v178, v179 offset1:1
	s_waitcnt vmcnt(8)
	ds_write2_b32 v109, v180, v181 offset1:1
	v_add_u32_e32 v108, 0x410, v14
	v_add_u32_e32 v109, 0x618, v14
	v_add_u32_e32 v110, 0x820, v14
	v_add_u32_e32 v111, 0xa28, v14
	v_add_u32_e32 v112, 0xc30, v14
	v_add_u32_e32 v113, 0xe38, v14
	s_waitcnt vmcnt(7)
	ds_write2_b32 v14, v182, v183 offset1:1
	s_waitcnt vmcnt(6)
	ds_write2_b32 v110, v184, v185 offset1:1
	s_waitcnt vmcnt(5)
	ds_write2_b32 v111, v186, v187 offset1:1
	s_waitcnt vmcnt(4)
	ds_write2_b32 v112, v188, v189 offset1:1
	s_waitcnt vmcnt(3)
	ds_write2_b32 v113, v190, v191 offset1:1
	s_waitcnt vmcnt(2)
	ds_write2_b32 v14, v192, v193 offset0:130 offset1:131
	v_add_u32_e32 v14, 0x1040, v14
	s_waitcnt vmcnt(1)
	ds_write2_b32 v108, v194, v195 offset1:1
	s_waitcnt vmcnt(0)
	ds_write2_b32 v109, v196, v197 offset1:1
	s_and_b32 s0, 0xffff, s4
	s_cmp_gt_u32 s0, 60
	s_waitcnt lgkmcnt(0)
	s_cselect_b32 s0, 0xc0, 0
	s_and_b32 s1, 0xffff, s3
	v_add_u32_e32 v12, 0x400, v81
	ds_read2_b32 v[216:217], v81 offset1:65
	ds_read2_b32 v[218:219], v81 offset0:130 offset1:195
	ds_read2_b32 v[220:221], v12 offset0:4 offset1:69
	ds_read2_b32 v[222:223], v12 offset0:134 offset1:199
	ds_read2_b32 v[224:225], v81 offset0:8 offset1:73
	ds_read2_b32 v[226:227], v81 offset0:138 offset1:203
	ds_read2_b32 v[228:229], v12 offset0:12 offset1:77
	s_and_b32 s2, 0xffff, s2
	s_add_i32 s0, s0, s1
	s_waitcnt lgkmcnt(6)
	v_cvt_pk_bf16_f32 v2, v216, v217
	ds_read2_b32 v[230:231], v12 offset0:142 offset1:207
	s_lshl_b32 s8, s2, 1
	v_or_b32_e32 v10, s0, v80
	s_waitcnt lgkmcnt(6)
	v_cvt_pk_bf16_f32 v3, v218, v219
	ds_read2_b32 v[216:217], v81 offset0:16 offset1:81
	v_lshl_add_u64 v[8:9], v[44:45], 0, s[8:9]
	v_lshlrev_b32_e32 v14, 12, v10
	s_waitcnt lgkmcnt(6)
	v_cvt_pk_bf16_f32 v4, v220, v221
	ds_read2_b32 v[218:219], v81 offset0:146 offset1:211
	s_waitcnt lgkmcnt(6)
	v_cvt_pk_bf16_f32 v5, v222, v223
	v_lshl_add_u64 v[10:11], v[8:9], 0, v[14:15]
	ds_read2_b32 v[220:221], v12 offset0:20 offset1:85
	global_store_dwordx4 v[10:11], v[2:5], off
	v_or_b32_e32 v10, s0, v82
	v_lshlrev_b32_e32 v14, 12, v10
	s_waitcnt lgkmcnt(6)
	v_cvt_pk_bf16_f32 v2, v224, v225
	ds_read2_b32 v[222:223], v12 offset0:150 offset1:215
	s_waitcnt lgkmcnt(6)
	v_cvt_pk_bf16_f32 v3, v226, v227
	ds_read2_b32 v[224:225], v81 offset0:24 offset1:89
	s_waitcnt lgkmcnt(6)
	v_cvt_pk_bf16_f32 v4, v228, v229
	ds_read2_b32 v[226:227], v81 offset0:154 offset1:219
	s_waitcnt lgkmcnt(6)
	v_cvt_pk_bf16_f32 v5, v230, v231
	v_lshl_add_u64 v[10:11], v[8:9], 0, v[14:15]
	ds_read2_b32 v[228:229], v12 offset0:28 offset1:93
	global_store_dwordx4 v[10:11], v[2:5], off
	v_or_b32_e32 v10, s0, v83
	v_lshlrev_b32_e32 v14, 12, v10
	s_waitcnt lgkmcnt(6)
	v_cvt_pk_bf16_f32 v2, v216, v217
	ds_read2_b32 v[230:231], v12 offset0:158 offset1:223
	s_waitcnt lgkmcnt(6)
	v_cvt_pk_bf16_f32 v3, v218, v219
	ds_read2_b32 v[216:217], v81 offset0:32 offset1:97
	s_waitcnt lgkmcnt(6)
	v_cvt_pk_bf16_f32 v4, v220, v221
	ds_read2_b32 v[218:219], v81 offset0:162 offset1:227
	s_waitcnt lgkmcnt(6)
	v_cvt_pk_bf16_f32 v5, v222, v223
	v_lshl_add_u64 v[10:11], v[8:9], 0, v[14:15]
	ds_read2_b32 v[220:221], v12 offset0:36 offset1:101
	global_store_dwordx4 v[10:11], v[2:5], off
	v_or_b32_e32 v10, s0, v84
	v_lshlrev_b32_e32 v14, 12, v10
	s_waitcnt lgkmcnt(6)
	v_cvt_pk_bf16_f32 v2, v224, v225
	ds_read2_b32 v[222:223], v12 offset0:166 offset1:231
	s_waitcnt lgkmcnt(6)
	v_cvt_pk_bf16_f32 v3, v226, v227
	ds_read2_b32 v[224:225], v81 offset0:40 offset1:105
	s_waitcnt lgkmcnt(6)
	v_cvt_pk_bf16_f32 v4, v228, v229
	ds_read2_b32 v[226:227], v81 offset0:170 offset1:235
	s_waitcnt lgkmcnt(6)
	v_cvt_pk_bf16_f32 v5, v230, v231
	v_lshl_add_u64 v[10:11], v[8:9], 0, v[14:15]
	ds_read2_b32 v[228:229], v12 offset0:44 offset1:109
	global_store_dwordx4 v[10:11], v[2:5], off
	v_or_b32_e32 v10, s0, v85
	v_lshlrev_b32_e32 v14, 12, v10
	s_waitcnt lgkmcnt(6)
	v_cvt_pk_bf16_f32 v2, v216, v217
	ds_read2_b32 v[230:231], v12 offset0:174 offset1:239
	s_waitcnt lgkmcnt(6)
	v_cvt_pk_bf16_f32 v3, v218, v219
	ds_read2_b32 v[216:217], v81 offset0:48 offset1:113
	s_waitcnt lgkmcnt(6)
	v_cvt_pk_bf16_f32 v4, v220, v221
	ds_read2_b32 v[218:219], v81 offset0:178 offset1:243
	s_waitcnt lgkmcnt(6)
	v_cvt_pk_bf16_f32 v5, v222, v223
	v_lshl_add_u64 v[10:11], v[8:9], 0, v[14:15]
	ds_read2_b32 v[220:221], v12 offset0:52 offset1:117
	global_store_dwordx4 v[10:11], v[2:5], off
	v_or_b32_e32 v10, s0, v86
	v_lshlrev_b32_e32 v14, 12, v10
	s_waitcnt lgkmcnt(6)
	v_cvt_pk_bf16_f32 v2, v224, v225
	ds_read2_b32 v[222:223], v12 offset0:182 offset1:247
	s_waitcnt lgkmcnt(6)
	v_cvt_pk_bf16_f32 v3, v226, v227
	ds_read2_b32 v[224:225], v81 offset0:56 offset1:121
	s_waitcnt lgkmcnt(6)
	v_cvt_pk_bf16_f32 v4, v228, v229
	ds_read2_b32 v[226:227], v81 offset0:186 offset1:251
	s_waitcnt lgkmcnt(6)
	v_cvt_pk_bf16_f32 v5, v230, v231
	v_lshl_add_u64 v[10:11], v[8:9], 0, v[14:15]
	ds_read2_b32 v[228:229], v12 offset0:60 offset1:125
	global_store_dwordx4 v[10:11], v[2:5], off
	v_or_b32_e32 v10, s0, v87
	v_lshlrev_b32_e32 v14, 12, v10
	s_waitcnt lgkmcnt(6)
	v_cvt_pk_bf16_f32 v2, v216, v217
	ds_read2_b32 v[230:231], v12 offset0:190 offset1:255
	s_waitcnt lgkmcnt(6)
	v_cvt_pk_bf16_f32 v3, v218, v219
	s_waitcnt lgkmcnt(5)
	v_cvt_pk_bf16_f32 v4, v220, v221
	s_waitcnt lgkmcnt(4)
	v_cvt_pk_bf16_f32 v5, v222, v223
	v_lshl_add_u64 v[10:11], v[8:9], 0, v[14:15]
	global_store_dwordx4 v[10:11], v[2:5], off
	s_nop 0
	s_waitcnt lgkmcnt(3)
	v_cvt_pk_bf16_f32 v2, v224, v225
	s_waitcnt lgkmcnt(2)
	v_cvt_pk_bf16_f32 v3, v226, v227
	s_waitcnt lgkmcnt(1)
	v_cvt_pk_bf16_f32 v4, v228, v229
	v_or_b32_e32 v5, s0, v88
	v_lshlrev_b32_e32 v14, 12, v5
	s_waitcnt lgkmcnt(0)
	v_cvt_pk_bf16_f32 v5, v230, v231
	v_lshl_add_u64 v[6:7], v[8:9], 0, v[14:15]
	global_store_dwordx4 v[6:7], v[2:5], off
